# hand-written S part 2 (packed query pairs, bias folded, -1080 VALU instrs per wave-unit)
# speedup vs baseline: 1.0170x; 1.0170x over previous
; DI void unit_sample_attn2(int u, const bf16* __restrict__ Q, const float* __restrict__ ckw, const float* __restrict__ cvw, const float* __restrict__ nkw, const float* __restrict__ nvw, const bf16* __restrict__ G, bf16* __restrict__ MIX, ...
;     ...
;     for (int n0 = 0; n0 < 96; n0 += 32) {
;         f32x4 kv[16], vv[16]; float s[16];
; #pragma unroll
;         for (int i = 0; i < 16; ++i) { const int n = n0 + 2 * i + half, dlt = sub ? 16 * (33 + n) : 512 - 4 * n; const size_t ro = (size_t)(2048 + j1 - dlt) * 512;
;             kv[i] = __builtin_nontemporal_load((const f32x4*)(ck + ro)); }
; #pragma unroll
;         for (int i = 0; i < 16; ++i) { const int n = n0 + 2 * i + half, dlt = sub ? 16 * (33 + n) : 512 - 4 * n; const size_t ro = (size_t)(2048 + j1 - dlt) * 512;
;             vv[i] = __builtin_nontemporal_load((const f32x4*)(cv + ro)); }
.LBB0_733:
	v_add_u32_e32 v8, 0x1e0, v173
	v_cndmask_b32_e64 v8, v8, v171, s[4:5]
	v_add_u32_e32 v8, s94, v8
	v_ashrrev_i32_e32 v9, 31, v8
	v_lshlrev_b64 v[8:9], 11, v[8:9]
	v_lshl_add_u64 v[10:11], v[156:157], 0, v[8:9]
	global_load_dwordx4 v[132:135], v[10:11], off nt
	v_add_u32_e32 v10, 0x1c0, v173
	v_add_u32_e32 v11, 8, v171
	v_cndmask_b32_e64 v10, v10, v11, s[4:5]
	v_add_u32_e32 v10, s94, v10
	v_ashrrev_i32_e32 v11, 31, v10
	v_lshlrev_b64 v[10:11], 11, v[10:11]
	v_lshl_add_u64 v[12:13], v[156:157], 0, v[10:11]
	global_load_dwordx4 v[128:131], v[12:13], off nt
	v_add_u32_e32 v12, 0x1a0, v173
	v_add_u32_e32 v13, 16, v171
	v_cndmask_b32_e64 v12, v12, v13, s[4:5]
	v_add_u32_e32 v12, s94, v12
	v_ashrrev_i32_e32 v13, 31, v12
	v_lshlrev_b64 v[12:13], 11, v[12:13]
	v_lshl_add_u64 v[14:15], v[156:157], 0, v[12:13]
	global_load_dwordx4 v[124:127], v[14:15], off nt
	v_add_u32_e32 v14, 0x180, v173
	v_add_u32_e32 v15, 24, v171
	v_cndmask_b32_e64 v14, v14, v15, s[4:5]
	v_add_u32_e32 v14, s94, v14
	v_ashrrev_i32_e32 v15, 31, v14
	v_lshlrev_b64 v[14:15], 11, v[14:15]
	v_lshl_add_u64 v[16:17], v[156:157], 0, v[14:15]
	global_load_dwordx4 v[120:123], v[16:17], off nt
	v_add_u32_e32 v16, 0x160, v173
	v_add_u32_e32 v17, 32, v171
	v_cndmask_b32_e64 v16, v16, v17, s[4:5]
	v_add_u32_e32 v16, s94, v16
	v_ashrrev_i32_e32 v17, 31, v16
	v_lshlrev_b64 v[16:17], 11, v[16:17]
	v_lshl_add_u64 v[18:19], v[156:157], 0, v[16:17]
	global_load_dwordx4 v[116:119], v[18:19], off nt
	v_add_u32_e32 v18, 0x140, v173
	v_add_u32_e32 v19, 40, v171
	v_cndmask_b32_e64 v18, v18, v19, s[4:5]
	v_add_u32_e32 v18, s94, v18
	v_ashrrev_i32_e32 v19, 31, v18
	v_lshlrev_b64 v[18:19], 11, v[18:19]
	v_lshl_add_u64 v[20:21], v[156:157], 0, v[18:19]
	global_load_dwordx4 v[112:115], v[20:21], off nt
	v_add_u32_e32 v20, 0x120, v173
	v_add_u32_e32 v21, 48, v171
	v_cndmask_b32_e64 v20, v20, v21, s[4:5]
	v_add_u32_e32 v20, s94, v20
	v_ashrrev_i32_e32 v21, 31, v20
	v_lshlrev_b64 v[20:21], 11, v[20:21]
	v_lshl_add_u64 v[22:23], v[156:157], 0, v[20:21]
	global_load_dwordx4 v[108:111], v[22:23], off nt
	v_add_u32_e32 v22, 0x100, v173
	v_add_u32_e32 v23, 56, v171
	v_cndmask_b32_e64 v22, v22, v23, s[4:5]
	v_add_u32_e32 v22, s94, v22
	v_ashrrev_i32_e32 v23, 31, v22
	v_lshlrev_b64 v[22:23], 11, v[22:23]
	v_lshl_add_u64 v[24:25], v[156:157], 0, v[22:23]
	global_load_dwordx4 v[104:107], v[24:25], off nt
	v_add_u32_e32 v24, 0xe0, v173
	v_add_u32_e32 v25, 64, v171
	v_cndmask_b32_e64 v24, v24, v25, s[4:5]
	v_add_u32_e32 v24, s94, v24
	v_ashrrev_i32_e32 v25, 31, v24
	v_lshlrev_b64 v[24:25], 11, v[24:25]
	v_lshl_add_u64 v[26:27], v[156:157], 0, v[24:25]
	global_load_dwordx4 v[100:103], v[26:27], off nt
	v_add_u32_e32 v26, 0xc0, v173
	v_add_u32_e32 v27, 0x48, v171
	v_cndmask_b32_e64 v26, v26, v27, s[4:5]
	v_add_u32_e32 v26, s94, v26
	v_ashrrev_i32_e32 v27, 31, v26
	v_lshlrev_b64 v[26:27], 11, v[26:27]
	v_lshl_add_u64 v[28:29], v[156:157], 0, v[26:27]
	global_load_dwordx4 v[96:99], v[28:29], off nt
	v_add_u32_e32 v28, 0xa0, v173
	v_add_u32_e32 v29, 0x50, v171
	v_cndmask_b32_e64 v28, v28, v29, s[4:5]
	v_add_u32_e32 v28, s94, v28
	v_ashrrev_i32_e32 v29, 31, v28
	v_lshlrev_b64 v[28:29], 11, v[28:29]
	v_lshl_add_u64 v[30:31], v[156:157], 0, v[28:29]
	global_load_dwordx4 v[92:95], v[30:31], off nt
	v_add_u32_e32 v30, 0x80, v173
	v_add_u32_e32 v31, 0x58, v171
	v_cndmask_b32_e64 v30, v30, v31, s[4:5]
	v_add_u32_e32 v30, s94, v30
	v_ashrrev_i32_e32 v31, 31, v30
	v_lshlrev_b64 v[176:177], 11, v[30:31]
	v_lshl_add_u64 v[30:31], v[156:157], 0, v[176:177]
	global_load_dwordx4 v[88:91], v[30:31], off nt
	v_add_u32_e32 v30, 0x60, v173
	v_add_u32_e32 v31, 0x60, v171
	v_cndmask_b32_e64 v30, v30, v31, s[4:5]
	v_add_u32_e32 v30, s94, v30
	v_ashrrev_i32_e32 v31, 31, v30
	v_lshlrev_b64 v[178:179], 11, v[30:31]
	v_lshl_add_u64 v[30:31], v[156:157], 0, v[178:179]
	v_mov_b32_e32 v174, v87
	v_mov_b32_e32 v175, v85
	global_load_dwordx4 v[84:87], v[30:31], off nt
	v_add_u32_e32 v30, 64, v173
	v_add_u32_e32 v31, 0x68, v171
	v_cndmask_b32_e64 v30, v30, v31, s[4:5]
	v_add_u32_e32 v30, s94, v30
	v_ashrrev_i32_e32 v31, 31, v30
	v_lshlrev_b64 v[180:181], 11, v[30:31]
	v_lshl_add_u64 v[30:31], v[156:157], 0, v[180:181]
	global_load_dwordx4 v[80:83], v[30:31], off nt
	v_add_u32_e32 v30, 32, v173
	v_add_u32_e32 v31, 0x70, v171
	v_cndmask_b32_e64 v30, v30, v31, s[4:5]
	v_lshl_add_u64 v[8:9], v[154:155], 0, v[8:9]
	v_add_u32_e32 v30, s94, v30
	global_load_dwordx4 v[68:71], v[8:9], off nt
	v_lshl_add_u64 v[8:9], v[154:155], 0, v[10:11]
	v_ashrrev_i32_e32 v31, 31, v30
	global_load_dwordx4 v[64:67], v[8:9], off nt
	v_lshl_add_u64 v[8:9], v[154:155], 0, v[12:13]
	v_lshlrev_b64 v[184:185], 11, v[30:31]
	global_load_dwordx4 v[60:63], v[8:9], off nt
	v_lshl_add_u64 v[8:9], v[154:155], 0, v[14:15]
	v_lshl_add_u64 v[30:31], v[156:157], 0, v[184:185]
	global_load_dwordx4 v[56:59], v[8:9], off nt
	v_lshl_add_u64 v[8:9], v[154:155], 0, v[16:17]
	global_load_dwordx4 v[76:79], v[30:31], off nt
	v_add_u32_e32 v30, 0x78, v171
	global_load_dwordx4 v[52:55], v[8:9], off nt
	v_lshl_add_u64 v[8:9], v[154:155], 0, v[18:19]
	v_cndmask_b32_e64 v30, v173, v30, s[4:5]
	global_load_dwordx4 v[48:51], v[8:9], off nt
	v_lshl_add_u64 v[8:9], v[154:155], 0, v[20:21]
	v_add_u32_e32 v30, s94, v30
	global_load_dwordx4 v[44:47], v[8:9], off nt
	v_lshl_add_u64 v[8:9], v[154:155], 0, v[22:23]
	v_ashrrev_i32_e32 v31, 31, v30
	global_load_dwordx4 v[40:43], v[8:9], off nt
	v_lshl_add_u64 v[8:9], v[154:155], 0, v[24:25]
	v_lshlrev_b64 v[186:187], 11, v[30:31]
	global_load_dwordx4 v[36:39], v[8:9], off nt
	v_lshl_add_u64 v[8:9], v[154:155], 0, v[26:27]
	v_lshl_add_u64 v[30:31], v[156:157], 0, v[186:187]
	global_load_dwordx4 v[32:35], v[8:9], off nt
	v_lshl_add_u64 v[8:9], v[154:155], 0, v[28:29]
	global_load_dwordx4 v[72:75], v[30:31], off nt
	s_waitcnt vmcnt(25)
; DI float dot16(f32x4 a, f32x4 b) { float d = (a[0] * b[0] + a[1] * b[1]) + (a[2] * b[2] + a[3] * b[3]); d += __shfl_xor(d, 1); d += __shfl_xor(d, 2); d += __shfl_xor(d, 4); d += __shfl_xor(d, 8); return d; }
; DI void unit_sample_attn2(int u, const bf16* __restrict__ Q, const float* __restrict__ ckw, const float* __restrict__ cvw, const float* __restrict__ nkw, const float* __restrict__ nvw, const bf16* __restrict__ G, bf16* __restrict__ MIX, ...
;     ...
;         for (int i = 0; i < 16; ++i) { const int n = n0 + 2 * i + half, dlt = sub ? 16 * (33 + n) : 512 - 4 * n; const size_t ro = (size_t)(2048 + j1 - dlt) * 512;
;             vv[i] = __builtin_nontemporal_load((const f32x4*)(cv + ro)); }
; #pragma unroll
;         for (int i = 0; i < 16; ++i) { const int n = n0 + 2 * i + half, dlt = sub ? 16 * (33 + n) : 512 - 4 * n;
;             s[i] = dot16(qs, kv[i]) - slope2 * (float)dlt + ((!sub && (dlt & 15) == 0) ? 1.f : 0.f); }
	v_pk_mul_f32 v[134:135], v[134:135], v[160:161]
	global_load_dwordx4 v[28:31], v[8:9], off nt
	v_lshl_add_u64 v[8:9], v[154:155], 0, v[176:177]
	v_add_u32_e32 v176, 0xfffffe20, v172
	v_add_u32_e32 v177, 0x78, v163
	v_pk_mul_f32 v[132:133], v[132:133], v[158:159]
	global_load_dwordx4 v[24:27], v[8:9], off nt
	v_lshl_add_u64 v[8:9], v[154:155], 0, v[178:179]
	v_cndmask_b32_e64 v178, v176, v177, s[4:5]
	v_pk_mov_b32 v[176:177], v[132:133], v[134:135] op_sel:[1,0]
	v_mov_b32_e32 v133, v135
	v_pk_add_f32 v[132:133], v[176:177], v[132:133]
	v_add_u32_e32 v134, 0x70, v163
	v_add_f32_e32 v132, v132, v133
	s_waitcnt vmcnt(26)
	v_pk_mul_f32 v[130:131], v[130:131], v[160:161]
	v_pk_mul_f32 v[128:129], v[128:129], v[158:159]
	s_waitcnt vmcnt(25)
	v_pk_mul_f32 v[126:127], v[126:127], v[160:161]
	v_pk_mul_f32 v[124:125], v[124:125], v[158:159]
	s_waitcnt lgkmcnt(0)
	v_add_f32_dpp v132, v132, v132 quad_perm:[1,0,3,2] row_mask:0xf bank_mask:0xf
	s_waitcnt vmcnt(24)
	v_pk_mul_f32 v[122:123], v[122:123], v[160:161]
	v_pk_mul_f32 v[120:121], v[120:121], v[158:159]
	s_waitcnt vmcnt(23)
	v_pk_mul_f32 v[118:119], v[118:119], v[160:161]
	v_pk_mul_f32 v[116:117], v[116:117], v[158:159]
	s_waitcnt lgkmcnt(0)
	v_add_f32_dpp v132, v132, v132 quad_perm:[2,3,0,1] row_mask:0xf bank_mask:0xf
	s_waitcnt vmcnt(22)
	v_pk_mul_f32 v[114:115], v[114:115], v[160:161]
	v_pk_mul_f32 v[112:113], v[112:113], v[158:159]
	s_waitcnt vmcnt(21)
	v_pk_mul_f32 v[110:111], v[110:111], v[160:161]
	v_pk_mul_f32 v[108:109], v[108:109], v[158:159]
	s_waitcnt lgkmcnt(0)
	v_add_f32_dpp v132, v132, v132 row_half_mirror row_mask:0xf bank_mask:0xf
	s_waitcnt vmcnt(20)
	v_pk_mul_f32 v[106:107], v[106:107], v[160:161]
	v_pk_mul_f32 v[104:105], v[104:105], v[158:159]
	s_waitcnt vmcnt(19)
	v_pk_mul_f32 v[102:103], v[102:103], v[160:161]
	v_pk_mul_f32 v[100:101], v[100:101], v[158:159]
	s_waitcnt lgkmcnt(0)
	v_add_f32_dpp v132, v132, v132 row_mirror row_mask:0xf bank_mask:0xf
	v_cvt_f32_i32_e32 v133, v178
	s_waitcnt vmcnt(18)
	v_pk_mul_f32 v[98:99], v[98:99], v[160:161]
	v_pk_mul_f32 v[96:97], v[96:97], v[158:159]
	s_waitcnt vmcnt(17)
	v_pk_mul_f32 v[94:95], v[94:95], v[160:161]
	v_fma_f32 v132, -v136, v133, v132
	v_and_b32_e32 v133, 12, v178
	v_cmp_eq_u32_e32 vcc, 0, v133
	s_and_b64 s[0:1], s[4:5], vcc
	v_cndmask_b32_e64 v133, 0, 1.0, s[0:1]
	v_add_f32_e32 v132, v133, v132
	v_add_u32_e32 v133, 0xfffffe40, v172
	v_cndmask_b32_e64 v133, v133, v134, s[4:5]
	v_pk_mov_b32 v[134:135], v[128:129], v[130:131] op_sel:[1,0]
	v_mov_b32_e32 v129, v131
	v_pk_add_f32 v[128:129], v[134:135], v[128:129]
	v_add_u32_e32 v130, 0x68, v163
	v_add_f32_e32 v128, v128, v129
	v_pk_mul_f32 v[92:93], v[92:93], v[158:159]
	s_waitcnt vmcnt(16)
	v_pk_mul_f32 v[90:91], v[90:91], v[160:161]
	v_pk_mul_f32 v[88:89], v[88:89], v[158:159]
	s_waitcnt vmcnt(15)
	v_pk_mul_f32 v[86:87], v[86:87], v[160:161]
	s_waitcnt lgkmcnt(0)
	v_add_f32_dpp v128, v128, v128 quad_perm:[1,0,3,2] row_mask:0xf bank_mask:0xf
	v_pk_mul_f32 v[84:85], v[84:85], v[158:159]
	s_waitcnt vmcnt(14)
	v_pk_mul_f32 v[82:83], v[82:83], v[160:161]
	v_pk_mul_f32 v[80:81], v[80:81], v[158:159]
	s_waitcnt vmcnt(9)
	v_pk_mul_f32 v[78:79], v[78:79], v[160:161]
	s_waitcnt lgkmcnt(0)
	v_add_f32_dpp v128, v128, v128 quad_perm:[2,3,0,1] row_mask:0xf bank_mask:0xf
	v_pk_mul_f32 v[76:77], v[76:77], v[158:159]
	global_load_dwordx4 v[20:23], v[8:9], off nt
	v_lshl_add_u64 v[8:9], v[154:155], 0, v[180:181]
	global_load_dwordx4 v[16:19], v[8:9], off nt
	s_waitcnt lgkmcnt(0)
	v_add_f32_dpp v128, v128, v128 row_half_mirror row_mask:0xf bank_mask:0xf
	v_lshl_add_u64 v[8:9], v[154:155], 0, v[184:185]
	global_load_dwordx4 v[12:15], v[8:9], off nt
	v_lshl_add_u64 v[8:9], v[154:155], 0, v[186:187]
	global_load_dwordx4 v[8:11], v[8:9], off nt
	s_waitcnt lgkmcnt(0)
	v_add_f32_dpp v128, v128, v128 row_mirror row_mask:0xf bank_mask:0xf
	v_cvt_f32_i32_e32 v129, v133
	s_waitcnt vmcnt(6)
	v_pk_mul_f32 v[74:75], v[74:75], v[160:161]
	v_pk_mul_f32 v[72:73], v[72:73], v[158:159]
	s_add_i32 s2, s2, 32
	v_fma_f32 v128, -v136, v129, v128
	v_and_b32_e32 v129, 12, v133
	v_cmp_eq_u32_e32 vcc, 0, v129
	s_and_b64 s[0:1], s[4:5], vcc
	v_cndmask_b32_e64 v129, 0, 1.0, s[0:1]
	v_add_f32_e32 v128, v129, v128
	v_add_u32_e32 v129, 0xfffffe60, v172
	v_cndmask_b32_e64 v129, v129, v130, s[4:5]
	v_pk_mov_b32 v[130:131], v[124:125], v[126:127] op_sel:[1,0]
	v_mov_b32_e32 v125, v127
	v_pk_add_f32 v[124:125], v[130:131], v[124:125]
	v_add_u32_e32 v126, 0x60, v163
	v_add_f32_e32 v124, v124, v125
	v_add_u32_e32 v171, 0x80, v171
	v_add_u32_e32 v173, 0xfffffe00, v173
	s_waitcnt lgkmcnt(0)
	v_add_f32_dpp v124, v124, v124 quad_perm:[1,0,3,2] row_mask:0xf bank_mask:0xf
	s_waitcnt lgkmcnt(0)
	s_nop 0
	v_add_f32_dpp v124, v124, v124 quad_perm:[2,3,0,1] row_mask:0xf bank_mask:0xf
	s_waitcnt lgkmcnt(0)
	s_nop 0
	v_add_f32_dpp v124, v124, v124 row_half_mirror row_mask:0xf bank_mask:0xf
	s_waitcnt lgkmcnt(0)
	s_nop 0
	v_add_f32_dpp v124, v124, v124 row_mirror row_mask:0xf bank_mask:0xf
	v_cvt_f32_i32_e32 v125, v129
	v_fma_f32 v124, -v136, v125, v124
	v_and_b32_e32 v125, 12, v129
	v_cmp_eq_u32_e32 vcc, 0, v125
	s_and_b64 s[0:1], s[4:5], vcc
	v_cndmask_b32_e64 v125, 0, 1.0, s[0:1]
	v_add_f32_e32 v124, v125, v124
	v_add_u32_e32 v125, 0xfffffe80, v172
	v_cndmask_b32_e64 v125, v125, v126, s[4:5]
	v_pk_mov_b32 v[126:127], v[120:121], v[122:123] op_sel:[1,0]
	v_mov_b32_e32 v121, v123
	v_pk_add_f32 v[120:121], v[126:127], v[120:121]
	v_add_u32_e32 v122, 0x58, v163
	v_add_f32_e32 v120, v120, v121
	s_waitcnt lgkmcnt(0)
	s_nop 0
	v_add_f32_dpp v120, v120, v120 quad_perm:[1,0,3,2] row_mask:0xf bank_mask:0xf
	s_waitcnt lgkmcnt(0)
; DI float dot16(f32x4 a, f32x4 b) { float d = (a[0] * b[0] + a[1] * b[1]) + (a[2] * b[2] + a[3] * b[3]); d += __shfl_xor(d, 1); d += __shfl_xor(d, 2); d += __shfl_xor(d, 4); d += __shfl_xor(d, 8); return d; }
; DI void unit_sample_attn2(int u, const bf16* __restrict__ Q, const float* __restrict__ ckw, const float* __restrict__ cvw, const float* __restrict__ nkw, const float* __restrict__ nvw, const bf16* __restrict__ G, bf16* __restrict__ MIX, ...
;     ...
;         for (int i = 0; i < 16; ++i) { const int n = n0 + 2 * i + half, dlt = sub ? 16 * (33 + n) : 512 - 4 * n;
;             s[i] = dot16(qs, kv[i]) - slope2 * (float)dlt + ((!sub && (dlt & 15) == 0) ? 1.f : 0.f); }
	s_nop 0
	v_add_f32_dpp v120, v120, v120 quad_perm:[2,3,0,1] row_mask:0xf bank_mask:0xf
	s_waitcnt lgkmcnt(0)
	s_nop 0
	v_add_f32_dpp v120, v120, v120 row_half_mirror row_mask:0xf bank_mask:0xf
	s_waitcnt lgkmcnt(0)
	s_nop 0
	v_add_f32_dpp v120, v120, v120 row_mirror row_mask:0xf bank_mask:0xf
	v_cvt_f32_i32_e32 v121, v125
	v_fma_f32 v120, -v136, v121, v120
	v_and_b32_e32 v121, 12, v125
	v_cmp_eq_u32_e32 vcc, 0, v121
	s_and_b64 s[0:1], s[4:5], vcc
	v_cndmask_b32_e64 v121, 0, 1.0, s[0:1]
	v_add_f32_e32 v120, v121, v120
	v_add_u32_e32 v121, 0xfffffea0, v172
	v_cndmask_b32_e64 v121, v121, v122, s[4:5]
	v_pk_mov_b32 v[122:123], v[116:117], v[118:119] op_sel:[1,0]
	v_mov_b32_e32 v117, v119
	v_pk_add_f32 v[116:117], v[122:123], v[116:117]
	v_add_u32_e32 v118, 0x50, v163
	v_add_f32_e32 v116, v116, v117
	s_waitcnt lgkmcnt(0)
	s_nop 0
	v_add_f32_dpp v116, v116, v116 quad_perm:[1,0,3,2] row_mask:0xf bank_mask:0xf
	s_waitcnt lgkmcnt(0)
	s_nop 0
	v_add_f32_dpp v116, v116, v116 quad_perm:[2,3,0,1] row_mask:0xf bank_mask:0xf
	s_waitcnt lgkmcnt(0)
	s_nop 0
	v_add_f32_dpp v116, v116, v116 row_half_mirror row_mask:0xf bank_mask:0xf
	s_waitcnt lgkmcnt(0)
	s_nop 0
	v_add_f32_dpp v116, v116, v116 row_mirror row_mask:0xf bank_mask:0xf
	v_cvt_f32_i32_e32 v117, v121
	v_fma_f32 v116, -v136, v117, v116
	v_and_b32_e32 v117, 12, v121
	v_cmp_eq_u32_e32 vcc, 0, v117
	s_and_b64 s[0:1], s[4:5], vcc
	v_cndmask_b32_e64 v117, 0, 1.0, s[0:1]
	v_add_f32_e32 v116, v117, v116
	v_add_u32_e32 v117, 0xfffffec0, v172
	v_cndmask_b32_e64 v117, v117, v118, s[4:5]
	v_pk_mov_b32 v[118:119], v[112:113], v[114:115] op_sel:[1,0]
	v_mov_b32_e32 v113, v115
	v_pk_add_f32 v[112:113], v[118:119], v[112:113]
	v_add_u32_e32 v114, 0x48, v163
	v_add_f32_e32 v112, v112, v113
	s_waitcnt lgkmcnt(0)
	s_nop 0
	v_add_f32_dpp v112, v112, v112 quad_perm:[1,0,3,2] row_mask:0xf bank_mask:0xf
	s_waitcnt lgkmcnt(0)
	s_nop 0
	v_add_f32_dpp v112, v112, v112 quad_perm:[2,3,0,1] row_mask:0xf bank_mask:0xf
	s_waitcnt lgkmcnt(0)
	s_nop 0
	v_add_f32_dpp v112, v112, v112 row_half_mirror row_mask:0xf bank_mask:0xf
	s_waitcnt lgkmcnt(0)
	s_nop 0
	v_add_f32_dpp v112, v112, v112 row_mirror row_mask:0xf bank_mask:0xf
	v_cvt_f32_i32_e32 v113, v117
	v_fma_f32 v112, -v136, v113, v112
	v_and_b32_e32 v113, 12, v117
	v_cmp_eq_u32_e32 vcc, 0, v113
	s_and_b64 s[0:1], s[4:5], vcc
	v_cndmask_b32_e64 v113, 0, 1.0, s[0:1]
	v_add_f32_e32 v112, v113, v112
	v_add_u32_e32 v113, 0xfffffee0, v172
	v_cndmask_b32_e64 v113, v113, v114, s[4:5]
	v_pk_mov_b32 v[114:115], v[108:109], v[110:111] op_sel:[1,0]
	v_mov_b32_e32 v109, v111
	v_pk_add_f32 v[108:109], v[114:115], v[108:109]
	v_add_u32_e32 v110, 64, v163
	v_add_f32_e32 v108, v108, v109
	s_waitcnt lgkmcnt(0)
	s_nop 0
	v_add_f32_dpp v108, v108, v108 quad_perm:[1,0,3,2] row_mask:0xf bank_mask:0xf
	s_waitcnt lgkmcnt(0)
	s_nop 0
	v_add_f32_dpp v108, v108, v108 quad_perm:[2,3,0,1] row_mask:0xf bank_mask:0xf
	s_waitcnt lgkmcnt(0)
	s_nop 0
	v_add_f32_dpp v108, v108, v108 row_half_mirror row_mask:0xf bank_mask:0xf
	s_waitcnt lgkmcnt(0)
	s_nop 0
	v_add_f32_dpp v108, v108, v108 row_mirror row_mask:0xf bank_mask:0xf
	v_cvt_f32_i32_e32 v109, v113
	v_fma_f32 v108, -v136, v109, v108
	v_and_b32_e32 v109, 12, v113
	v_cmp_eq_u32_e32 vcc, 0, v109
	s_and_b64 s[0:1], s[4:5], vcc
	v_cndmask_b32_e64 v109, 0, 1.0, s[0:1]
	v_add_f32_e32 v108, v109, v108
	v_add_u32_e32 v109, 0xffffff00, v172
	v_cndmask_b32_e64 v109, v109, v110, s[4:5]
	v_pk_mov_b32 v[110:111], v[104:105], v[106:107] op_sel:[1,0]
	v_mov_b32_e32 v105, v107
	v_pk_add_f32 v[104:105], v[110:111], v[104:105]
	v_add_u32_e32 v106, 56, v163
	v_add_f32_e32 v104, v104, v105
	s_waitcnt lgkmcnt(0)
	s_nop 0
	v_add_f32_dpp v104, v104, v104 quad_perm:[1,0,3,2] row_mask:0xf bank_mask:0xf
	s_waitcnt lgkmcnt(0)
	s_nop 0
	v_add_f32_dpp v104, v104, v104 quad_perm:[2,3,0,1] row_mask:0xf bank_mask:0xf
	s_waitcnt lgkmcnt(0)
	s_nop 0
	v_add_f32_dpp v104, v104, v104 row_half_mirror row_mask:0xf bank_mask:0xf
	s_waitcnt lgkmcnt(0)
	s_nop 0
	v_add_f32_dpp v104, v104, v104 row_mirror row_mask:0xf bank_mask:0xf
	v_cvt_f32_i32_e32 v105, v109
	v_fma_f32 v104, -v136, v105, v104
	v_and_b32_e32 v105, 12, v109
	v_cmp_eq_u32_e32 vcc, 0, v105
	s_and_b64 s[0:1], s[4:5], vcc
	v_cndmask_b32_e64 v105, 0, 1.0, s[0:1]
	v_add_f32_e32 v104, v105, v104
	v_add_u32_e32 v105, 0xffffff20, v172
	v_cndmask_b32_e64 v105, v105, v106, s[4:5]
	v_pk_mov_b32 v[106:107], v[100:101], v[102:103] op_sel:[1,0]
	v_mov_b32_e32 v101, v103
	v_pk_add_f32 v[100:101], v[106:107], v[100:101]
	v_add_u32_e32 v102, 48, v163
	v_add_f32_e32 v100, v100, v101
	s_waitcnt lgkmcnt(0)
	s_nop 0
	v_add_f32_dpp v100, v100, v100 quad_perm:[1,0,3,2] row_mask:0xf bank_mask:0xf
	s_waitcnt lgkmcnt(0)
	s_nop 0
	v_add_f32_dpp v100, v100, v100 quad_perm:[2,3,0,1] row_mask:0xf bank_mask:0xf
	s_waitcnt lgkmcnt(0)
	s_nop 0
	v_add_f32_dpp v100, v100, v100 row_half_mirror row_mask:0xf bank_mask:0xf
	s_waitcnt lgkmcnt(0)
	s_nop 0
	v_add_f32_dpp v100, v100, v100 row_mirror row_mask:0xf bank_mask:0xf
	v_cvt_f32_i32_e32 v101, v105
	v_fma_f32 v100, -v136, v101, v100
	v_and_b32_e32 v101, 12, v105
	v_cmp_eq_u32_e32 vcc, 0, v101
	s_and_b64 s[0:1], s[4:5], vcc
	v_cndmask_b32_e64 v101, 0, 1.0, s[0:1]
	v_add_f32_e32 v100, v101, v100
	v_add_u32_e32 v101, 0xffffff40, v172
	v_cndmask_b32_e64 v101, v101, v102, s[4:5]
	v_pk_mov_b32 v[102:103], v[96:97], v[98:99] op_sel:[1,0]
	v_mov_b32_e32 v97, v99
	v_pk_add_f32 v[96:97], v[102:103], v[96:97]
	v_add_u32_e32 v98, 40, v163
	v_add_f32_e32 v96, v96, v97
	s_waitcnt lgkmcnt(0)
	s_nop 0
	v_add_f32_dpp v96, v96, v96 quad_perm:[1,0,3,2] row_mask:0xf bank_mask:0xf
	s_waitcnt lgkmcnt(0)
; DI float dot16(f32x4 a, f32x4 b) { float d = (a[0] * b[0] + a[1] * b[1]) + (a[2] * b[2] + a[3] * b[3]); d += __shfl_xor(d, 1); d += __shfl_xor(d, 2); d += __shfl_xor(d, 4); d += __shfl_xor(d, 8); return d; }
; DI void unit_sample_attn2(int u, const bf16* __restrict__ Q, const float* __restrict__ ckw, const float* __restrict__ cvw, const float* __restrict__ nkw, const float* __restrict__ nvw, const bf16* __restrict__ G, bf16* __restrict__ MIX, ...
;     ...
;         for (int i = 0; i < 16; ++i) { const int n = n0 + 2 * i + half, dlt = sub ? 16 * (33 + n) : 512 - 4 * n;
;             s[i] = dot16(qs, kv[i]) - slope2 * (float)dlt + ((!sub && (dlt & 15) == 0) ? 1.f : 0.f); }
	s_nop 0
	v_add_f32_dpp v96, v96, v96 quad_perm:[2,3,0,1] row_mask:0xf bank_mask:0xf
	s_waitcnt lgkmcnt(0)
	s_nop 0
	v_add_f32_dpp v96, v96, v96 row_half_mirror row_mask:0xf bank_mask:0xf
	s_waitcnt lgkmcnt(0)
	s_nop 0
	v_add_f32_dpp v96, v96, v96 row_mirror row_mask:0xf bank_mask:0xf
	v_cvt_f32_i32_e32 v97, v101
	v_fma_f32 v96, -v136, v97, v96
	v_and_b32_e32 v97, 12, v101
	v_cmp_eq_u32_e32 vcc, 0, v97
	s_and_b64 s[0:1], s[4:5], vcc
	v_cndmask_b32_e64 v97, 0, 1.0, s[0:1]
	v_add_f32_e32 v96, v97, v96
	v_add_u32_e32 v97, 0xffffff60, v172
	v_cndmask_b32_e64 v97, v97, v98, s[4:5]
	v_pk_mov_b32 v[98:99], v[92:93], v[94:95] op_sel:[1,0]
	v_mov_b32_e32 v93, v95
	v_pk_add_f32 v[92:93], v[98:99], v[92:93]
	v_add_u32_e32 v94, 32, v163
	v_add_f32_e32 v92, v92, v93
	s_waitcnt lgkmcnt(0)
	s_nop 0
	v_add_f32_dpp v92, v92, v92 quad_perm:[1,0,3,2] row_mask:0xf bank_mask:0xf
	s_waitcnt lgkmcnt(0)
	s_nop 0
	v_add_f32_dpp v92, v92, v92 quad_perm:[2,3,0,1] row_mask:0xf bank_mask:0xf
	s_waitcnt lgkmcnt(0)
	s_nop 0
	v_add_f32_dpp v92, v92, v92 row_half_mirror row_mask:0xf bank_mask:0xf
	s_waitcnt lgkmcnt(0)
	s_nop 0
	v_add_f32_dpp v92, v92, v92 row_mirror row_mask:0xf bank_mask:0xf
	v_cvt_f32_i32_e32 v93, v97
	v_fma_f32 v92, -v136, v93, v92
	v_and_b32_e32 v93, 12, v97
	v_cmp_eq_u32_e32 vcc, 0, v93
	s_and_b64 s[0:1], s[4:5], vcc
	v_cndmask_b32_e64 v93, 0, 1.0, s[0:1]
	v_add_f32_e32 v92, v93, v92
	v_add_u32_e32 v93, 0xffffff80, v172
	v_cndmask_b32_e64 v93, v93, v94, s[4:5]
	v_pk_mov_b32 v[94:95], v[88:89], v[90:91] op_sel:[1,0]
	v_mov_b32_e32 v89, v91
	v_pk_add_f32 v[88:89], v[94:95], v[88:89]
	v_add_u32_e32 v90, 24, v163
	v_add_f32_e32 v88, v88, v89
	s_waitcnt lgkmcnt(0)
	s_nop 0
	v_add_f32_dpp v88, v88, v88 quad_perm:[1,0,3,2] row_mask:0xf bank_mask:0xf
	s_waitcnt lgkmcnt(0)
	s_nop 0
	v_add_f32_dpp v88, v88, v88 quad_perm:[2,3,0,1] row_mask:0xf bank_mask:0xf
	s_waitcnt lgkmcnt(0)
	s_nop 0
	v_add_f32_dpp v88, v88, v88 row_half_mirror row_mask:0xf bank_mask:0xf
	s_waitcnt lgkmcnt(0)
	s_nop 0
	v_add_f32_dpp v88, v88, v88 row_mirror row_mask:0xf bank_mask:0xf
	v_cvt_f32_i32_e32 v89, v93
	v_fma_f32 v88, -v136, v89, v88
	v_and_b32_e32 v89, 12, v93
	v_cmp_eq_u32_e32 vcc, 0, v89
	s_and_b64 s[0:1], s[4:5], vcc
	v_cndmask_b32_e64 v89, 0, 1.0, s[0:1]
	v_add_f32_e32 v88, v89, v88
	v_add_u32_e32 v89, 0xffffffa0, v172
	v_cndmask_b32_e64 v89, v89, v90, s[4:5]
	v_pk_mov_b32 v[90:91], v[84:85], v[86:87] op_sel:[1,0]
	v_mov_b32_e32 v85, v87
	v_pk_add_f32 v[84:85], v[90:91], v[84:85]
	s_nop 0
	v_add_f32_e32 v84, v84, v85
	s_waitcnt lgkmcnt(0)
	s_nop 0
	v_add_f32_dpp v84, v84, v84 quad_perm:[1,0,3,2] row_mask:0xf bank_mask:0xf
	s_waitcnt lgkmcnt(0)
	s_nop 0
	v_add_f32_dpp v84, v84, v84 quad_perm:[2,3,0,1] row_mask:0xf bank_mask:0xf
	s_waitcnt lgkmcnt(0)
	s_nop 0
	v_add_f32_dpp v84, v84, v84 row_half_mirror row_mask:0xf bank_mask:0xf
	s_waitcnt lgkmcnt(0)
	s_nop 0
	v_add_f32_dpp v84, v84, v84 row_mirror row_mask:0xf bank_mask:0xf
	v_cvt_f32_i32_e32 v85, v89
	v_fma_f32 v84, -v136, v85, v84
	v_and_b32_e32 v85, 12, v89
	v_cmp_eq_u32_e32 vcc, 0, v85
	s_and_b64 s[0:1], s[4:5], vcc
	v_cndmask_b32_e64 v85, 0, 1.0, s[0:1]
	v_add_f32_e32 v86, v85, v84
	v_subrev_u32_e32 v84, 64, v172
	v_add_u32_e32 v85, 16, v163
	v_cndmask_b32_e64 v87, v84, v85, s[4:5]
	v_pk_mov_b32 v[84:85], v[80:81], v[82:83] op_sel:[1,0]
	v_mov_b32_e32 v81, v83
	v_pk_add_f32 v[80:81], v[84:85], v[80:81]
	s_nop 0
	v_add_f32_e32 v80, v80, v81
	s_waitcnt lgkmcnt(0)
	s_nop 0
	v_add_f32_dpp v80, v80, v80 quad_perm:[1,0,3,2] row_mask:0xf bank_mask:0xf
	s_waitcnt lgkmcnt(0)
	s_nop 0
	v_add_f32_dpp v80, v80, v80 quad_perm:[2,3,0,1] row_mask:0xf bank_mask:0xf
	s_waitcnt lgkmcnt(0)
	s_nop 0
	v_add_f32_dpp v80, v80, v80 row_half_mirror row_mask:0xf bank_mask:0xf
	s_waitcnt lgkmcnt(0)
	s_nop 0
	v_add_f32_dpp v80, v80, v80 row_mirror row_mask:0xf bank_mask:0xf
	v_cvt_f32_i32_e32 v81, v87
	v_fma_f32 v80, -v136, v81, v80
	v_and_b32_e32 v81, 12, v87
	v_cmp_eq_u32_e32 vcc, 0, v81
	s_and_b64 s[0:1], s[4:5], vcc
	v_cndmask_b32_e64 v81, 0, 1.0, s[0:1]
	v_add_f32_e32 v82, v81, v80
	v_subrev_u32_e32 v80, 32, v172
	v_add_u32_e32 v81, 8, v163
	v_cndmask_b32_e64 v83, v80, v81, s[4:5]
	v_pk_mov_b32 v[80:81], v[76:77], v[78:79] op_sel:[1,0]
	v_mov_b32_e32 v77, v79
	v_pk_add_f32 v[76:77], v[80:81], v[76:77]
	v_cndmask_b32_e64 v79, v172, v163, s[4:5]
	v_add_f32_e32 v76, v76, v77
	v_add_u32_e32 v163, 0xffffff80, v163
	v_add_u32_e32 v172, 0x200, v172
	s_waitcnt lgkmcnt(0)
	v_add_f32_dpp v76, v76, v76 quad_perm:[1,0,3,2] row_mask:0xf bank_mask:0xf
	s_waitcnt lgkmcnt(0)
	s_nop 0
	v_add_f32_dpp v76, v76, v76 quad_perm:[2,3,0,1] row_mask:0xf bank_mask:0xf
	s_waitcnt lgkmcnt(0)
	s_nop 0
	v_add_f32_dpp v76, v76, v76 row_half_mirror row_mask:0xf bank_mask:0xf
	s_waitcnt lgkmcnt(0)
	s_nop 0
	v_add_f32_dpp v76, v76, v76 row_mirror row_mask:0xf bank_mask:0xf
	v_cvt_f32_i32_e32 v77, v83
	v_fma_f32 v76, -v136, v77, v76
	v_and_b32_e32 v77, 12, v83
	v_cmp_eq_u32_e32 vcc, 0, v77
	s_and_b64 s[0:1], s[4:5], vcc
	v_cndmask_b32_e64 v77, 0, 1.0, s[0:1]
	v_add_f32_e32 v78, v77, v76
	v_pk_mov_b32 v[76:77], v[72:73], v[74:75] op_sel:[1,0]
	v_mov_b32_e32 v73, v75
	v_pk_add_f32 v[72:73], v[76:77], v[72:73]
	s_nop 0
	v_add_f32_e32 v72, v72, v73
	s_waitcnt lgkmcnt(0)
	s_nop 0
	v_add_f32_dpp v72, v72, v72 quad_perm:[1,0,3,2] row_mask:0xf bank_mask:0xf
	s_waitcnt lgkmcnt(0)
	s_nop 0
	v_add_f32_dpp v72, v72, v72 quad_perm:[2,3,0,1] row_mask:0xf bank_mask:0xf
	s_waitcnt lgkmcnt(0)
	s_nop 0
	v_add_f32_dpp v72, v72, v72 row_half_mirror row_mask:0xf bank_mask:0xf
	s_waitcnt lgkmcnt(0)
; DI float fexp2(float x) { return __builtin_amdgcn_exp2f(x); }
; DI void unit_sample_attn2(int u, const bf16* __restrict__ Q, const float* __restrict__ ckw, const float* __restrict__ cvw, const float* __restrict__ nkw, const float* __restrict__ nvw, const bf16* __restrict__ G, bf16* __restrict__ MIX, ...
;     ...
;         float mn = mB;
; #pragma unroll
;         for (int i = 0; i < 16; ++i) mn = fmaxf(mn, s[i]);
;         const float alpha = fexp2(mB - mn); float ps = 0.f; f32x4 acc = oB * alpha;
; #pragma unroll
;         for (int i = 0; i < 16; ++i) { const float p = fexp2(s[i] - mn); ps += p; acc += vv[i] * p; }
;         lB = lB * alpha + ps; mB = mn; oB = acc;
	s_nop 0
	v_add_f32_dpp v72, v72, v72 row_mirror row_mask:0xf bank_mask:0xf
	v_cvt_f32_i32_e32 v73, v79
	v_fma_f32 v72, -v136, v73, v72
	v_and_b32_e32 v73, 12, v79
	v_cmp_eq_u32_e32 vcc, 0, v73
	s_and_b64 s[0:1], s[4:5], vcc
	v_cndmask_b32_e64 v73, 0, 1.0, s[0:1]
	v_add_f32_e32 v73, v73, v72
	v_max3_f32 v72, v175, v132, v128
	v_max3_f32 v72, v72, v124, v120
	v_max3_f32 v72, v72, v116, v112
	v_max3_f32 v72, v72, v108, v104
	v_max3_f32 v72, v72, v100, v96
	v_max3_f32 v72, v72, v92, v88
	v_max3_f32 v72, v72, v86, v82
	v_max3_f32 v85, v72, v78, v73
	v_sub_f32_e32 v74, v132, v85
	v_exp_f32_e32 v74, v74
	v_sub_f32_e32 v72, v175, v85
	v_exp_f32_e32 v72, v72
	s_cmp_gt_u32 s2, 63
	v_add_f32_e32 v75, 0, v74
	v_pk_mul_f32 v[68:69], v[68:69], v[74:75] op_sel_hi:[1,0]
	v_pk_mul_f32 v[70:71], v[70:71], v[74:75] op_sel_hi:[1,0]
	v_pk_fma_f32 v[4:5], v[4:5], v[72:73], v[68:69] op_sel_hi:[1,0,1]
	v_sub_f32_e32 v68, v128, v85
	v_exp_f32_e32 v68, v68
	v_pk_fma_f32 v[6:7], v[6:7], v[72:73], v[70:71] op_sel_hi:[1,0,1]
	v_add_f32_e32 v69, v68, v75
	v_pk_fma_f32 v[4:5], v[64:65], v[68:69], v[4:5] op_sel_hi:[1,0,1]
	v_sub_f32_e32 v64, v124, v85
	v_exp_f32_e32 v64, v64
	v_pk_fma_f32 v[6:7], v[66:67], v[68:69], v[6:7] op_sel_hi:[1,0,1]
	v_add_f32_e32 v65, v64, v69
	v_pk_fma_f32 v[4:5], v[60:61], v[64:65], v[4:5] op_sel_hi:[1,0,1]
	v_sub_f32_e32 v60, v120, v85
	v_exp_f32_e32 v60, v60
	v_pk_fma_f32 v[6:7], v[62:63], v[64:65], v[6:7] op_sel_hi:[1,0,1]
	v_add_f32_e32 v61, v60, v65
	v_pk_fma_f32 v[4:5], v[56:57], v[60:61], v[4:5] op_sel_hi:[1,0,1]
	v_sub_f32_e32 v56, v116, v85
	v_exp_f32_e32 v56, v56
	v_pk_fma_f32 v[6:7], v[58:59], v[60:61], v[6:7] op_sel_hi:[1,0,1]
	v_add_f32_e32 v57, v56, v61
	v_pk_fma_f32 v[4:5], v[52:53], v[56:57], v[4:5] op_sel_hi:[1,0,1]
	v_sub_f32_e32 v52, v112, v85
	v_exp_f32_e32 v52, v52
	v_pk_fma_f32 v[6:7], v[54:55], v[56:57], v[6:7] op_sel_hi:[1,0,1]
	v_add_f32_e32 v53, v52, v57
	v_pk_fma_f32 v[4:5], v[48:49], v[52:53], v[4:5] op_sel_hi:[1,0,1]
	v_sub_f32_e32 v48, v108, v85
	v_exp_f32_e32 v48, v48
	v_pk_fma_f32 v[6:7], v[50:51], v[52:53], v[6:7] op_sel_hi:[1,0,1]
	v_add_f32_e32 v49, v48, v53
	v_pk_fma_f32 v[4:5], v[44:45], v[48:49], v[4:5] op_sel_hi:[1,0,1]
	v_sub_f32_e32 v44, v104, v85
	v_exp_f32_e32 v44, v44
	v_pk_fma_f32 v[6:7], v[46:47], v[48:49], v[6:7] op_sel_hi:[1,0,1]
	v_add_f32_e32 v45, v44, v49
	v_pk_fma_f32 v[4:5], v[40:41], v[44:45], v[4:5] op_sel_hi:[1,0,1]
	v_sub_f32_e32 v40, v100, v85
	v_exp_f32_e32 v40, v40
	v_pk_fma_f32 v[6:7], v[42:43], v[44:45], v[6:7] op_sel_hi:[1,0,1]
	v_add_f32_e32 v41, v40, v45
	v_pk_fma_f32 v[4:5], v[36:37], v[40:41], v[4:5] op_sel_hi:[1,0,1]
	v_sub_f32_e32 v36, v96, v85
	v_exp_f32_e32 v36, v36
	v_pk_fma_f32 v[6:7], v[38:39], v[40:41], v[6:7] op_sel_hi:[1,0,1]
	v_add_f32_e32 v37, v36, v41
	v_pk_fma_f32 v[4:5], v[32:33], v[36:37], v[4:5] op_sel_hi:[1,0,1]
	v_sub_f32_e32 v32, v92, v85
	v_exp_f32_e32 v32, v32
	v_pk_fma_f32 v[6:7], v[34:35], v[36:37], v[6:7] op_sel_hi:[1,0,1]
	v_add_f32_e32 v33, v32, v37
	s_waitcnt vmcnt(5)
	v_pk_fma_f32 v[4:5], v[28:29], v[32:33], v[4:5] op_sel_hi:[1,0,1]
	v_sub_f32_e32 v28, v88, v85
	v_exp_f32_e32 v28, v28
	v_pk_fma_f32 v[6:7], v[30:31], v[32:33], v[6:7] op_sel_hi:[1,0,1]
	v_add_f32_e32 v29, v28, v33
	s_waitcnt vmcnt(4)
	v_pk_fma_f32 v[4:5], v[24:25], v[28:29], v[4:5] op_sel_hi:[1,0,1]
	v_sub_f32_e32 v24, v86, v85
	v_exp_f32_e32 v24, v24
	v_pk_fma_f32 v[6:7], v[26:27], v[28:29], v[6:7] op_sel_hi:[1,0,1]
	v_add_f32_e32 v25, v24, v29
	s_waitcnt vmcnt(3)
	v_pk_fma_f32 v[4:5], v[20:21], v[24:25], v[4:5] op_sel_hi:[1,0,1]
	v_sub_f32_e32 v20, v82, v85
	v_exp_f32_e32 v20, v20
	v_pk_fma_f32 v[6:7], v[22:23], v[24:25], v[6:7] op_sel_hi:[1,0,1]
	v_add_f32_e32 v21, v20, v25
	s_waitcnt vmcnt(2)
	v_pk_fma_f32 v[4:5], v[16:17], v[20:21], v[4:5] op_sel_hi:[1,0,1]
	v_sub_f32_e32 v16, v78, v85
	v_exp_f32_e32 v16, v16
	v_pk_fma_f32 v[6:7], v[18:19], v[20:21], v[6:7] op_sel_hi:[1,0,1]
	v_add_f32_e32 v17, v16, v21
	s_waitcnt vmcnt(1)
	v_pk_fma_f32 v[4:5], v[12:13], v[16:17], v[4:5] op_sel_hi:[1,0,1]
	v_sub_f32_e32 v12, v73, v85
	v_exp_f32_e32 v12, v12
	v_pk_fma_f32 v[6:7], v[14:15], v[16:17], v[6:7] op_sel_hi:[1,0,1]
	v_add_f32_e32 v87, v12, v17
	s_waitcnt vmcnt(0)
	v_pk_fma_f32 v[6:7], v[10:11], v[12:13], v[6:7] op_sel_hi:[1,0,1]
	v_pk_fma_f32 v[4:5], v[8:9], v[12:13], v[4:5] op_sel_hi:[1,0,1]
	v_fmac_f32_e32 v87, v174, v72
	s_cbranch_scc0 .LBB0_733
; DI float dot16(f32x4 a, f32x4 b) { float d = (a[0] * b[0] + a[1] * b[1]) + (a[2] * b[2] + a[3] * b[3]); d += __shfl_xor(d, 1); d += __shfl_xor(d, 2); d += __shfl_xor(d, 4); d += __shfl_xor(d, 8); return d; }
; DI void unit_sample_attn2(int u, const bf16* __restrict__ Q, const float* __restrict__ ckw, const float* __restrict__ cvw, const float* __restrict__ nkw, const float* __restrict__ nvw, const bf16* __restrict__ G, bf16* __restrict__ MIX, ...
;     ...
;     {   f32x4 kv[9], vv[9]; int idxs[9];
; #pragma unroll
;         for (int i = 0; i < 9; ++i) { int idx = 1920 + wave + 8 * (2 * i + half); idxs[i] = idx; if (idx > 2051) idx = 2051;
;             const float* kp = (idx < 2048) ? ck + (size_t)idx * 512 : nk + (size_t)(idx - 2048) * 512;
;             const float* vp = (idx < 2048) ? cv + (size_t)idx * 512 : nv + (size_t)(idx - 2048) * 512;
;             kv[i] = __builtin_nontemporal_load((const f32x4*)kp); vv[i] = __builtin_nontemporal_load((const f32x4*)vp); }
; #pragma unroll
;         for (int jj = 0; jj < 4; ++jj) { float s[9]; float mn = NEG;
; #pragma unroll
;             for (int i = 0; i < 9; ++i) { const int dlt = 2048 + jj - idxs[i];
;                 const int cnt = (dlt <= 128 ? 1 : 0) + ((dlt & 3) == 0 ? 1 : 0) + ((dlt & 15) == 0 ? 1 : 0);
;                 const float lc = (cnt == 3) ? 1.5849625f : (cnt == 2) ? 1.f : 0.f;
;                 const float d = dot16(q[jj], kv[i]);
;                 s[i] = (idxs[i] > 2051 || dlt < 0 || cnt == 0) ? NEG : d - slope2 * (float)dlt + lc; mn = fmaxf(mn, s[i]); }
	s_lshl_b64 s[0:1], s[6:7], 22
	v_readlane_b32 s8, v247, 8
	v_readlane_b32 s9, v247, 9
	v_readlane_b32 s10, v247, 10
	v_readlane_b32 s11, v247, 11
	v_readlane_b32 s16, v247, 62
	v_readlane_b32 s17, v247, 56
	s_add_u32 s8, s8, s0
	s_addc_u32 s9, s9, s1
	s_add_u32 s10, s10, s0
	s_addc_u32 s11, s11, s1
	s_lshl_b32 s12, s16, 11
	s_add_u32 s8, s8, s12
	s_addc_u32 s9, s9, 0
	s_add_u32 s10, s10, s12
	s_addc_u32 s11, s11, 0
	v_lshl_add_u32 v80, v170, 14, v162
	s_sub_u32 s16, s16, 0x780
	v_lshl_add_u32 v82, v170, 3, s16
	v_min_u32_e32 v81, 3, v82
	v_lshl_add_u32 v81, v81, 11, v162
	global_load_dwordx4 v[44:47], v80, s[8:9] nt
	s_add_u32 s8, s8, 0x8000
	s_addc_u32 s9, s9, 0
	global_load_dwordx4 v[48:51], v80, s[8:9] nt
	s_add_u32 s8, s8, 0x8000
	s_addc_u32 s9, s9, 0
	global_load_dwordx4 v[52:55], v80, s[8:9] nt
	s_add_u32 s8, s8, 0x8000
	s_addc_u32 s9, s9, 0
	global_load_dwordx4 v[56:59], v80, s[8:9] nt
	s_add_u32 s8, s8, 0x8000
	s_addc_u32 s9, s9, 0
	global_load_dwordx4 v[60:63], v80, s[8:9] nt
	s_add_u32 s8, s8, 0x8000
	s_addc_u32 s9, s9, 0
	global_load_dwordx4 v[64:67], v80, s[8:9] nt
	s_add_u32 s8, s8, 0x8000
	s_addc_u32 s9, s9, 0
	global_load_dwordx4 v[68:71], v80, s[8:9] nt
	s_add_u32 s8, s8, 0x8000
	s_addc_u32 s9, s9, 0
	global_load_dwordx4 v[72:75], v80, s[8:9] nt
	s_lshl_b64 s[0:1], s[6:7], 13
	v_readlane_b32 s13, v246, 3
	v_readlane_b32 s14, v246, 9
	v_readlane_b32 s15, v246, 7
	s_add_u32 s12, s63, s0
	s_addc_u32 s13, s13, s1
	s_add_u32 s14, s14, s0
	s_addc_u32 s15, s15, s1
	global_load_dwordx4 v[76:79], v81, s[12:13] nt
	global_load_dwordx4 v[8:11], v80, s[10:11] nt
	s_add_u32 s10, s10, 0x8000
	s_addc_u32 s11, s11, 0
	global_load_dwordx4 v[12:15], v80, s[10:11] nt
	s_add_u32 s10, s10, 0x8000
	s_addc_u32 s11, s11, 0
	global_load_dwordx4 v[16:19], v80, s[10:11] nt
	s_add_u32 s10, s10, 0x8000
	s_addc_u32 s11, s11, 0
	global_load_dwordx4 v[20:23], v80, s[10:11] nt
	s_add_u32 s10, s10, 0x8000
	s_addc_u32 s11, s11, 0
	global_load_dwordx4 v[24:27], v80, s[10:11] nt
	s_add_u32 s10, s10, 0x8000
	s_addc_u32 s11, s11, 0
	global_load_dwordx4 v[28:31], v80, s[10:11] nt
	s_add_u32 s10, s10, 0x8000
	s_addc_u32 s11, s11, 0
	global_load_dwordx4 v[32:35], v80, s[10:11] nt
	s_add_u32 s10, s10, 0x8000
	s_addc_u32 s11, s11, 0
	global_load_dwordx4 v[36:39], v80, s[10:11] nt
	global_load_dwordx4 v[40:43], v81, s[14:15] nt
	v_mov_b32_e32 v188, v152
	v_mov_b32_e32 v189, v148
	v_mov_b32_e32 v190, v144
	v_mov_b32_e32 v191, v140
	v_mov_b32_e32 v192, v150
	v_mov_b32_e32 v193, v146
	v_mov_b32_e32 v194, v142
	v_mov_b32_e32 v195, v138
	v_mov_b32_e32 v196, v151
	v_mov_b32_e32 v197, v147
	v_mov_b32_e32 v198, v143
	v_mov_b32_e32 v199, v139
	v_mov_b32_e32 v200, v153
	v_mov_b32_e32 v201, v149
	v_mov_b32_e32 v202, v145
	v_mov_b32_e32 v203, v141
	v_add_u32_e32 v91, s17, v170
	v_lshlrev_b32_e32 v93, 2, v164
	v_lshl_add_u32 v83, v91, 11, v93
	v_lshl_add_u32 v84, v91, 9, v93
	v_lshlrev_b32_e32 v86, 2, v137
	v_lshl_add_u32 v118, v91, 3, v86
	v_lshl_add_u32 v86, v91, 5, v86
	v_and_b32_e32 v163, 15, v169
	v_cmp_eq_u32_e64 s[20:21], 0, v163
	v_sub_u32_e32 v163, 0x80, v82
	v_cvt_f32_i32_e32 v163, v163
	v_mul_f32_e32 v108, 0x3d800000, v136
	v_mov_b32_e32 v109, v163
	v_subrev_u32_e32 v110, 0, v82
	v_and_b32_e32 v110, 3, v110
	v_cmp_eq_u32_e64 s[18:19], 0, v110
	v_cmp_eq_u32_e32 vcc, 0, v82
	v_mov_b32_e32 v104, 0x3d800000
	s_nop 0
	v_cndmask_b32_e64 v110, v2, v104, s[18:19]
	v_mov_b32_e32 v104, 0x3dcae00d
	v_cndmask_b32_e32 v110, v110, v104, vcc
	v_fma_f32 v104, -v108, v109, v110
	v_cmp_le_u32_e32 vcc, 0, v82
	v_mov_b32_e32 v109, 0xef49f2ca
	s_nop 0
	v_cndmask_b32_e32 v110, v109, v104, vcc
	v_add_f32_e32 v109, 1.0, v163
	v_subrev_u32_e32 v111, 1, v82
	v_and_b32_e32 v111, 3, v111
	v_cmp_eq_u32_e64 s[18:19], 0, v111
	v_cmp_eq_u32_e32 vcc, 1, v82
	v_mov_b32_e32 v105, 0x3d800000
	s_nop 0
	v_cndmask_b32_e64 v111, v2, v105, s[18:19]
	v_mov_b32_e32 v105, 0x3dcae00d
	v_cndmask_b32_e32 v111, v111, v105, vcc
	v_fma_f32 v105, -v108, v109, v111
	v_cmp_le_u32_e32 vcc, 1, v82
	v_mov_b32_e32 v109, 0xef49f2ca
	s_nop 0
	v_cndmask_b32_e32 v111, v109, v105, vcc
	v_add_f32_e32 v109, 2.0, v163
	v_subrev_u32_e32 v112, 2, v82
	v_and_b32_e32 v112, 3, v112
	v_cmp_eq_u32_e64 s[18:19], 0, v112
	v_cmp_eq_u32_e32 vcc, 2, v82
	v_mov_b32_e32 v106, 0x3d800000
	s_nop 0
	v_cndmask_b32_e64 v112, v2, v106, s[18:19]
	v_mov_b32_e32 v106, 0x3dcae00d
	v_cndmask_b32_e32 v112, v112, v106, vcc
	v_fma_f32 v106, -v108, v109, v112
	v_cmp_le_u32_e32 vcc, 2, v82
	v_mov_b32_e32 v109, 0xef49f2ca
	s_nop 0
	v_cndmask_b32_e32 v112, v109, v106, vcc
	v_add_f32_e32 v109, 0x40400000, v163
	v_subrev_u32_e32 v113, 3, v82
	v_and_b32_e32 v113, 3, v113
	v_cmp_eq_u32_e64 s[18:19], 0, v113
	v_cmp_eq_u32_e32 vcc, 3, v82
	v_mov_b32_e32 v107, 0x3d800000
	s_nop 0
	v_cndmask_b32_e64 v113, v2, v107, s[18:19]
	v_mov_b32_e32 v107, 0x3dcae00d
	v_cndmask_b32_e32 v113, v113, v107, vcc
	v_fma_f32 v107, -v108, v109, v113
	v_cmp_le_u32_e32 vcc, 3, v82
	v_mov_b32_e32 v109, 0xef49f2ca
	s_nop 0
	v_cndmask_b32_e32 v113, v109, v107, vcc
	s_waitcnt vmcnt(17)
; DI float dot16(f32x4 a, f32x4 b) { float d = (a[0] * b[0] + a[1] * b[1]) + (a[2] * b[2] + a[3] * b[3]); d += __shfl_xor(d, 1); d += __shfl_xor(d, 2); d += __shfl_xor(d, 4); d += __shfl_xor(d, 8); return d; }
; DI void unit_sample_attn2(int u, const bf16* __restrict__ Q, const float* __restrict__ ckw, const float* __restrict__ cvw, const float* __restrict__ nkw, const float* __restrict__ nvw, const bf16* __restrict__ G, bf16* __restrict__ MIX, ...
;     ...
;             for (int i = 0; i < 9; ++i) { const int dlt = 2048 + jj - idxs[i];
;                 const int cnt = (dlt <= 128 ? 1 : 0) + ((dlt & 3) == 0 ? 1 : 0) + ((dlt & 15) == 0 ? 1 : 0);
;                 const float lc = (cnt == 3) ? 1.5849625f : (cnt == 2) ? 1.f : 0.f;
;                 const float d = dot16(q[jj], kv[i]);
;                 s[i] = (idxs[i] > 2051 || dlt < 0 || cnt == 0) ? NEG : d - slope2 * (float)dlt + lc; mn = fmaxf(mn, s[i]); }
	v_pk_fma_f32 v[204:205], v[44:45], v[188:189], v[110:111] op_sel_hi:[0,1,1]
	v_pk_fma_f32 v[204:205], v[44:45], v[192:193], v[204:205] op_sel:[1,0,0]
	v_pk_fma_f32 v[204:205], v[46:47], v[196:197], v[204:205] op_sel_hi:[0,1,1]
	v_pk_fma_f32 v[204:205], v[46:47], v[200:201], v[204:205] op_sel:[1,0,0]
	v_pk_fma_f32 v[206:207], v[44:45], v[190:191], v[112:113] op_sel_hi:[0,1,1]
	v_pk_fma_f32 v[206:207], v[44:45], v[194:195], v[206:207] op_sel:[1,0,0]
	v_pk_fma_f32 v[206:207], v[46:47], v[198:199], v[206:207] op_sel_hi:[0,1,1]
	v_pk_fma_f32 v[206:207], v[46:47], v[202:203], v[206:207] op_sel:[1,0,0]
	s_nop 0
	v_add_f32_dpp v204, v204, v204 quad_perm:[1,0,3,2] row_mask:0xf bank_mask:0xf
	v_add_f32_dpp v205, v205, v205 quad_perm:[1,0,3,2] row_mask:0xf bank_mask:0xf
	v_add_f32_dpp v206, v206, v206 quad_perm:[1,0,3,2] row_mask:0xf bank_mask:0xf
	v_add_f32_dpp v207, v207, v207 quad_perm:[1,0,3,2] row_mask:0xf bank_mask:0xf
	v_add_f32_dpp v204, v204, v204 quad_perm:[2,3,0,1] row_mask:0xf bank_mask:0xf
	v_add_f32_dpp v205, v205, v205 quad_perm:[2,3,0,1] row_mask:0xf bank_mask:0xf
	v_add_f32_dpp v206, v206, v206 quad_perm:[2,3,0,1] row_mask:0xf bank_mask:0xf
	v_add_f32_dpp v207, v207, v207 quad_perm:[2,3,0,1] row_mask:0xf bank_mask:0xf
	v_add_f32_dpp v204, v204, v204 row_half_mirror row_mask:0xf bank_mask:0xf
	v_add_f32_dpp v205, v205, v205 row_half_mirror row_mask:0xf bank_mask:0xf
	v_add_f32_dpp v206, v206, v206 row_half_mirror row_mask:0xf bank_mask:0xf
	v_add_f32_dpp v207, v207, v207 row_half_mirror row_mask:0xf bank_mask:0xf
	v_add_f32_dpp v204, v204, v204 row_mirror row_mask:0xf bank_mask:0xf
	v_add_f32_dpp v205, v205, v205 row_mirror row_mask:0xf bank_mask:0xf
	v_add_f32_dpp v206, v206, v206 row_mirror row_mask:0xf bank_mask:0xf
	v_add_f32_dpp v207, v207, v207 row_mirror row_mask:0xf bank_mask:0xf
	s_waitcnt vmcnt(16)
	v_pk_add_f32 v[104:105], v[104:105], v[136:137] op_sel_hi:[1,0]
	v_pk_add_f32 v[106:107], v[106:107], v[136:137] op_sel_hi:[1,0]
	v_pk_fma_f32 v[208:209], v[48:49], v[188:189], v[104:105] op_sel_hi:[0,1,1]
	v_pk_fma_f32 v[208:209], v[48:49], v[192:193], v[208:209] op_sel:[1,0,0]
	v_pk_fma_f32 v[208:209], v[50:51], v[196:197], v[208:209] op_sel_hi:[0,1,1]
	v_pk_fma_f32 v[208:209], v[50:51], v[200:201], v[208:209] op_sel:[1,0,0]
	v_pk_fma_f32 v[210:211], v[48:49], v[190:191], v[106:107] op_sel_hi:[0,1,1]
	v_pk_fma_f32 v[210:211], v[48:49], v[194:195], v[210:211] op_sel:[1,0,0]
	v_pk_fma_f32 v[210:211], v[50:51], v[198:199], v[210:211] op_sel_hi:[0,1,1]
	v_pk_fma_f32 v[210:211], v[50:51], v[202:203], v[210:211] op_sel:[1,0,0]
	s_nop 0
	v_add_f32_dpp v208, v208, v208 quad_perm:[1,0,3,2] row_mask:0xf bank_mask:0xf
	v_add_f32_dpp v209, v209, v209 quad_perm:[1,0,3,2] row_mask:0xf bank_mask:0xf
	v_add_f32_dpp v210, v210, v210 quad_perm:[1,0,3,2] row_mask:0xf bank_mask:0xf
	v_add_f32_dpp v211, v211, v211 quad_perm:[1,0,3,2] row_mask:0xf bank_mask:0xf
	v_add_f32_dpp v208, v208, v208 quad_perm:[2,3,0,1] row_mask:0xf bank_mask:0xf
	v_add_f32_dpp v209, v209, v209 quad_perm:[2,3,0,1] row_mask:0xf bank_mask:0xf
	v_add_f32_dpp v210, v210, v210 quad_perm:[2,3,0,1] row_mask:0xf bank_mask:0xf
	v_add_f32_dpp v211, v211, v211 quad_perm:[2,3,0,1] row_mask:0xf bank_mask:0xf
	v_add_f32_dpp v208, v208, v208 row_half_mirror row_mask:0xf bank_mask:0xf
	v_add_f32_dpp v209, v209, v209 row_half_mirror row_mask:0xf bank_mask:0xf
	v_add_f32_dpp v210, v210, v210 row_half_mirror row_mask:0xf bank_mask:0xf
	v_add_f32_dpp v211, v211, v211 row_half_mirror row_mask:0xf bank_mask:0xf
	v_add_f32_dpp v208, v208, v208 row_mirror row_mask:0xf bank_mask:0xf
	v_add_f32_dpp v209, v209, v209 row_mirror row_mask:0xf bank_mask:0xf
	v_add_f32_dpp v210, v210, v210 row_mirror row_mask:0xf bank_mask:0xf
	v_add_f32_dpp v211, v211, v211 row_mirror row_mask:0xf bank_mask:0xf
	s_waitcnt vmcnt(15)
	v_pk_add_f32 v[104:105], v[104:105], v[136:137] op_sel_hi:[1,0]
	v_pk_add_f32 v[106:107], v[106:107], v[136:137] op_sel_hi:[1,0]
	v_pk_fma_f32 v[212:213], v[52:53], v[188:189], v[104:105] op_sel_hi:[0,1,1]
	v_pk_fma_f32 v[212:213], v[52:53], v[192:193], v[212:213] op_sel:[1,0,0]
	v_pk_fma_f32 v[212:213], v[54:55], v[196:197], v[212:213] op_sel_hi:[0,1,1]
	v_pk_fma_f32 v[212:213], v[54:55], v[200:201], v[212:213] op_sel:[1,0,0]
	v_pk_fma_f32 v[214:215], v[52:53], v[190:191], v[106:107] op_sel_hi:[0,1,1]
	v_pk_fma_f32 v[214:215], v[52:53], v[194:195], v[214:215] op_sel:[1,0,0]
	v_pk_fma_f32 v[214:215], v[54:55], v[198:199], v[214:215] op_sel_hi:[0,1,1]
	v_pk_fma_f32 v[214:215], v[54:55], v[202:203], v[214:215] op_sel:[1,0,0]
	s_nop 0
	v_add_f32_dpp v212, v212, v212 quad_perm:[1,0,3,2] row_mask:0xf bank_mask:0xf
	v_add_f32_dpp v213, v213, v213 quad_perm:[1,0,3,2] row_mask:0xf bank_mask:0xf
	v_add_f32_dpp v214, v214, v214 quad_perm:[1,0,3,2] row_mask:0xf bank_mask:0xf
	v_add_f32_dpp v215, v215, v215 quad_perm:[1,0,3,2] row_mask:0xf bank_mask:0xf
	v_add_f32_dpp v212, v212, v212 quad_perm:[2,3,0,1] row_mask:0xf bank_mask:0xf
	v_add_f32_dpp v213, v213, v213 quad_perm:[2,3,0,1] row_mask:0xf bank_mask:0xf
	v_add_f32_dpp v214, v214, v214 quad_perm:[2,3,0,1] row_mask:0xf bank_mask:0xf
	v_add_f32_dpp v215, v215, v215 quad_perm:[2,3,0,1] row_mask:0xf bank_mask:0xf
	v_add_f32_dpp v212, v212, v212 row_half_mirror row_mask:0xf bank_mask:0xf
	v_add_f32_dpp v213, v213, v213 row_half_mirror row_mask:0xf bank_mask:0xf
	v_add_f32_dpp v214, v214, v214 row_half_mirror row_mask:0xf bank_mask:0xf
	v_add_f32_dpp v215, v215, v215 row_half_mirror row_mask:0xf bank_mask:0xf
	v_add_f32_dpp v212, v212, v212 row_mirror row_mask:0xf bank_mask:0xf
	v_add_f32_dpp v213, v213, v213 row_mirror row_mask:0xf bank_mask:0xf
	v_add_f32_dpp v214, v214, v214 row_mirror row_mask:0xf bank_mask:0xf
	v_add_f32_dpp v215, v215, v215 row_mirror row_mask:0xf bank_mask:0xf
	s_waitcnt vmcnt(14)
; DI float dot16(f32x4 a, f32x4 b) { float d = (a[0] * b[0] + a[1] * b[1]) + (a[2] * b[2] + a[3] * b[3]); d += __shfl_xor(d, 1); d += __shfl_xor(d, 2); d += __shfl_xor(d, 4); d += __shfl_xor(d, 8); return d; }
; DI void unit_sample_attn2(int u, const bf16* __restrict__ Q, const float* __restrict__ ckw, const float* __restrict__ cvw, const float* __restrict__ nkw, const float* __restrict__ nvw, const bf16* __restrict__ G, bf16* __restrict__ MIX, ...
;     ...
;             for (int i = 0; i < 9; ++i) { const int dlt = 2048 + jj - idxs[i];
;                 const int cnt = (dlt <= 128 ? 1 : 0) + ((dlt & 3) == 0 ? 1 : 0) + ((dlt & 15) == 0 ? 1 : 0);
;                 const float lc = (cnt == 3) ? 1.5849625f : (cnt == 2) ? 1.f : 0.f;
;                 const float d = dot16(q[jj], kv[i]);
;                 s[i] = (idxs[i] > 2051 || dlt < 0 || cnt == 0) ? NEG : d - slope2 * (float)dlt + lc; mn = fmaxf(mn, s[i]); }
	v_pk_add_f32 v[104:105], v[104:105], v[136:137] op_sel_hi:[1,0]
	v_pk_add_f32 v[106:107], v[106:107], v[136:137] op_sel_hi:[1,0]
	v_pk_fma_f32 v[216:217], v[56:57], v[188:189], v[104:105] op_sel_hi:[0,1,1]
	v_pk_fma_f32 v[216:217], v[56:57], v[192:193], v[216:217] op_sel:[1,0,0]
	v_pk_fma_f32 v[216:217], v[58:59], v[196:197], v[216:217] op_sel_hi:[0,1,1]
	v_pk_fma_f32 v[216:217], v[58:59], v[200:201], v[216:217] op_sel:[1,0,0]
	v_pk_fma_f32 v[218:219], v[56:57], v[190:191], v[106:107] op_sel_hi:[0,1,1]
	v_pk_fma_f32 v[218:219], v[56:57], v[194:195], v[218:219] op_sel:[1,0,0]
	v_pk_fma_f32 v[218:219], v[58:59], v[198:199], v[218:219] op_sel_hi:[0,1,1]
	v_pk_fma_f32 v[218:219], v[58:59], v[202:203], v[218:219] op_sel:[1,0,0]
	s_nop 0
	v_add_f32_dpp v216, v216, v216 quad_perm:[1,0,3,2] row_mask:0xf bank_mask:0xf
	v_add_f32_dpp v217, v217, v217 quad_perm:[1,0,3,2] row_mask:0xf bank_mask:0xf
	v_add_f32_dpp v218, v218, v218 quad_perm:[1,0,3,2] row_mask:0xf bank_mask:0xf
	v_add_f32_dpp v219, v219, v219 quad_perm:[1,0,3,2] row_mask:0xf bank_mask:0xf
	v_add_f32_dpp v216, v216, v216 quad_perm:[2,3,0,1] row_mask:0xf bank_mask:0xf
	v_add_f32_dpp v217, v217, v217 quad_perm:[2,3,0,1] row_mask:0xf bank_mask:0xf
	v_add_f32_dpp v218, v218, v218 quad_perm:[2,3,0,1] row_mask:0xf bank_mask:0xf
	v_add_f32_dpp v219, v219, v219 quad_perm:[2,3,0,1] row_mask:0xf bank_mask:0xf
	v_add_f32_dpp v216, v216, v216 row_half_mirror row_mask:0xf bank_mask:0xf
	v_add_f32_dpp v217, v217, v217 row_half_mirror row_mask:0xf bank_mask:0xf
	v_add_f32_dpp v218, v218, v218 row_half_mirror row_mask:0xf bank_mask:0xf
	v_add_f32_dpp v219, v219, v219 row_half_mirror row_mask:0xf bank_mask:0xf
	v_add_f32_dpp v216, v216, v216 row_mirror row_mask:0xf bank_mask:0xf
	v_add_f32_dpp v217, v217, v217 row_mirror row_mask:0xf bank_mask:0xf
	v_add_f32_dpp v218, v218, v218 row_mirror row_mask:0xf bank_mask:0xf
	v_add_f32_dpp v219, v219, v219 row_mirror row_mask:0xf bank_mask:0xf
	s_waitcnt vmcnt(13)
	v_pk_add_f32 v[104:105], v[104:105], v[136:137] op_sel_hi:[1,0]
	v_pk_add_f32 v[106:107], v[106:107], v[136:137] op_sel_hi:[1,0]
	v_pk_fma_f32 v[220:221], v[60:61], v[188:189], v[104:105] op_sel_hi:[0,1,1]
	v_pk_fma_f32 v[220:221], v[60:61], v[192:193], v[220:221] op_sel:[1,0,0]
	v_pk_fma_f32 v[220:221], v[62:63], v[196:197], v[220:221] op_sel_hi:[0,1,1]
	v_pk_fma_f32 v[220:221], v[62:63], v[200:201], v[220:221] op_sel:[1,0,0]
	v_pk_fma_f32 v[222:223], v[60:61], v[190:191], v[106:107] op_sel_hi:[0,1,1]
	v_pk_fma_f32 v[222:223], v[60:61], v[194:195], v[222:223] op_sel:[1,0,0]
	v_pk_fma_f32 v[222:223], v[62:63], v[198:199], v[222:223] op_sel_hi:[0,1,1]
	v_pk_fma_f32 v[222:223], v[62:63], v[202:203], v[222:223] op_sel:[1,0,0]
	s_nop 0
	v_add_f32_dpp v220, v220, v220 quad_perm:[1,0,3,2] row_mask:0xf bank_mask:0xf
	v_add_f32_dpp v221, v221, v221 quad_perm:[1,0,3,2] row_mask:0xf bank_mask:0xf
	v_add_f32_dpp v222, v222, v222 quad_perm:[1,0,3,2] row_mask:0xf bank_mask:0xf
	v_add_f32_dpp v223, v223, v223 quad_perm:[1,0,3,2] row_mask:0xf bank_mask:0xf
	v_add_f32_dpp v220, v220, v220 quad_perm:[2,3,0,1] row_mask:0xf bank_mask:0xf
	v_add_f32_dpp v221, v221, v221 quad_perm:[2,3,0,1] row_mask:0xf bank_mask:0xf
	v_add_f32_dpp v222, v222, v222 quad_perm:[2,3,0,1] row_mask:0xf bank_mask:0xf
	v_add_f32_dpp v223, v223, v223 quad_perm:[2,3,0,1] row_mask:0xf bank_mask:0xf
	v_add_f32_dpp v220, v220, v220 row_half_mirror row_mask:0xf bank_mask:0xf
	v_add_f32_dpp v221, v221, v221 row_half_mirror row_mask:0xf bank_mask:0xf
	v_add_f32_dpp v222, v222, v222 row_half_mirror row_mask:0xf bank_mask:0xf
	v_add_f32_dpp v223, v223, v223 row_half_mirror row_mask:0xf bank_mask:0xf
	v_add_f32_dpp v220, v220, v220 row_mirror row_mask:0xf bank_mask:0xf
	v_add_f32_dpp v221, v221, v221 row_mirror row_mask:0xf bank_mask:0xf
	v_add_f32_dpp v222, v222, v222 row_mirror row_mask:0xf bank_mask:0xf
	v_add_f32_dpp v223, v223, v223 row_mirror row_mask:0xf bank_mask:0xf
	s_waitcnt vmcnt(12)
	v_pk_add_f32 v[104:105], v[104:105], v[136:137] op_sel_hi:[1,0]
	v_pk_add_f32 v[106:107], v[106:107], v[136:137] op_sel_hi:[1,0]
	v_pk_fma_f32 v[224:225], v[64:65], v[188:189], v[104:105] op_sel_hi:[0,1,1]
	v_pk_fma_f32 v[224:225], v[64:65], v[192:193], v[224:225] op_sel:[1,0,0]
	v_pk_fma_f32 v[224:225], v[66:67], v[196:197], v[224:225] op_sel_hi:[0,1,1]
	v_pk_fma_f32 v[224:225], v[66:67], v[200:201], v[224:225] op_sel:[1,0,0]
	v_pk_fma_f32 v[228:229], v[64:65], v[190:191], v[106:107] op_sel_hi:[0,1,1]
	v_pk_fma_f32 v[228:229], v[64:65], v[194:195], v[228:229] op_sel:[1,0,0]
	v_pk_fma_f32 v[228:229], v[66:67], v[198:199], v[228:229] op_sel_hi:[0,1,1]
	v_pk_fma_f32 v[228:229], v[66:67], v[202:203], v[228:229] op_sel:[1,0,0]
	s_nop 0
	v_add_f32_dpp v224, v224, v224 quad_perm:[1,0,3,2] row_mask:0xf bank_mask:0xf
	v_add_f32_dpp v225, v225, v225 quad_perm:[1,0,3,2] row_mask:0xf bank_mask:0xf
	v_add_f32_dpp v228, v228, v228 quad_perm:[1,0,3,2] row_mask:0xf bank_mask:0xf
	v_add_f32_dpp v229, v229, v229 quad_perm:[1,0,3,2] row_mask:0xf bank_mask:0xf
	v_add_f32_dpp v224, v224, v224 quad_perm:[2,3,0,1] row_mask:0xf bank_mask:0xf
	v_add_f32_dpp v225, v225, v225 quad_perm:[2,3,0,1] row_mask:0xf bank_mask:0xf
	v_add_f32_dpp v228, v228, v228 quad_perm:[2,3,0,1] row_mask:0xf bank_mask:0xf
	v_add_f32_dpp v229, v229, v229 quad_perm:[2,3,0,1] row_mask:0xf bank_mask:0xf
	v_add_f32_dpp v224, v224, v224 row_half_mirror row_mask:0xf bank_mask:0xf
	v_add_f32_dpp v225, v225, v225 row_half_mirror row_mask:0xf bank_mask:0xf
	v_add_f32_dpp v228, v228, v228 row_half_mirror row_mask:0xf bank_mask:0xf
	v_add_f32_dpp v229, v229, v229 row_half_mirror row_mask:0xf bank_mask:0xf
	v_add_f32_dpp v224, v224, v224 row_mirror row_mask:0xf bank_mask:0xf
	v_add_f32_dpp v225, v225, v225 row_mirror row_mask:0xf bank_mask:0xf
	v_add_f32_dpp v228, v228, v228 row_mirror row_mask:0xf bank_mask:0xf
	v_add_f32_dpp v229, v229, v229 row_mirror row_mask:0xf bank_mask:0xf
	s_waitcnt vmcnt(11)
; DI float dot16(f32x4 a, f32x4 b) { float d = (a[0] * b[0] + a[1] * b[1]) + (a[2] * b[2] + a[3] * b[3]); d += __shfl_xor(d, 1); d += __shfl_xor(d, 2); d += __shfl_xor(d, 4); d += __shfl_xor(d, 8); return d; }
; DI void unit_sample_attn2(int u, const bf16* __restrict__ Q, const float* __restrict__ ckw, const float* __restrict__ cvw, const float* __restrict__ nkw, const float* __restrict__ nvw, const bf16* __restrict__ G, bf16* __restrict__ MIX, ...
;     ...
;             for (int i = 0; i < 9; ++i) { const int dlt = 2048 + jj - idxs[i];
;                 const int cnt = (dlt <= 128 ? 1 : 0) + ((dlt & 3) == 0 ? 1 : 0) + ((dlt & 15) == 0 ? 1 : 0);
;                 const float lc = (cnt == 3) ? 1.5849625f : (cnt == 2) ? 1.f : 0.f;
;                 const float d = dot16(q[jj], kv[i]);
;                 s[i] = (idxs[i] > 2051 || dlt < 0 || cnt == 0) ? NEG : d - slope2 * (float)dlt + lc; mn = fmaxf(mn, s[i]); }
	v_pk_add_f32 v[104:105], v[104:105], v[136:137] op_sel_hi:[1,0]
	v_pk_add_f32 v[106:107], v[106:107], v[136:137] op_sel_hi:[1,0]
	v_pk_fma_f32 v[230:231], v[68:69], v[188:189], v[104:105] op_sel_hi:[0,1,1]
	v_pk_fma_f32 v[230:231], v[68:69], v[192:193], v[230:231] op_sel:[1,0,0]
	v_pk_fma_f32 v[230:231], v[70:71], v[196:197], v[230:231] op_sel_hi:[0,1,1]
	v_pk_fma_f32 v[230:231], v[70:71], v[200:201], v[230:231] op_sel:[1,0,0]
	v_pk_fma_f32 v[232:233], v[68:69], v[190:191], v[106:107] op_sel_hi:[0,1,1]
	v_pk_fma_f32 v[232:233], v[68:69], v[194:195], v[232:233] op_sel:[1,0,0]
	v_pk_fma_f32 v[232:233], v[70:71], v[198:199], v[232:233] op_sel_hi:[0,1,1]
	v_pk_fma_f32 v[232:233], v[70:71], v[202:203], v[232:233] op_sel:[1,0,0]
	s_nop 0
	v_add_f32_dpp v230, v230, v230 quad_perm:[1,0,3,2] row_mask:0xf bank_mask:0xf
	v_add_f32_dpp v231, v231, v231 quad_perm:[1,0,3,2] row_mask:0xf bank_mask:0xf
	v_add_f32_dpp v232, v232, v232 quad_perm:[1,0,3,2] row_mask:0xf bank_mask:0xf
	v_add_f32_dpp v233, v233, v233 quad_perm:[1,0,3,2] row_mask:0xf bank_mask:0xf
	v_add_f32_dpp v230, v230, v230 quad_perm:[2,3,0,1] row_mask:0xf bank_mask:0xf
	v_add_f32_dpp v231, v231, v231 quad_perm:[2,3,0,1] row_mask:0xf bank_mask:0xf
	v_add_f32_dpp v232, v232, v232 quad_perm:[2,3,0,1] row_mask:0xf bank_mask:0xf
	v_add_f32_dpp v233, v233, v233 quad_perm:[2,3,0,1] row_mask:0xf bank_mask:0xf
	v_add_f32_dpp v230, v230, v230 row_half_mirror row_mask:0xf bank_mask:0xf
	v_add_f32_dpp v231, v231, v231 row_half_mirror row_mask:0xf bank_mask:0xf
	v_add_f32_dpp v232, v232, v232 row_half_mirror row_mask:0xf bank_mask:0xf
	v_add_f32_dpp v233, v233, v233 row_half_mirror row_mask:0xf bank_mask:0xf
	v_add_f32_dpp v230, v230, v230 row_mirror row_mask:0xf bank_mask:0xf
	v_add_f32_dpp v231, v231, v231 row_mirror row_mask:0xf bank_mask:0xf
	v_add_f32_dpp v232, v232, v232 row_mirror row_mask:0xf bank_mask:0xf
	v_add_f32_dpp v233, v233, v233 row_mirror row_mask:0xf bank_mask:0xf
	s_waitcnt vmcnt(10)
	v_pk_add_f32 v[104:105], v[104:105], v[136:137] op_sel_hi:[1,0]
	v_pk_add_f32 v[106:107], v[106:107], v[136:137] op_sel_hi:[1,0]
	v_pk_fma_f32 v[234:235], v[72:73], v[188:189], v[104:105] op_sel_hi:[0,1,1]
	v_pk_fma_f32 v[234:235], v[72:73], v[192:193], v[234:235] op_sel:[1,0,0]
	v_pk_fma_f32 v[234:235], v[74:75], v[196:197], v[234:235] op_sel_hi:[0,1,1]
	v_pk_fma_f32 v[234:235], v[74:75], v[200:201], v[234:235] op_sel:[1,0,0]
	v_pk_fma_f32 v[236:237], v[72:73], v[190:191], v[106:107] op_sel_hi:[0,1,1]
	v_pk_fma_f32 v[236:237], v[72:73], v[194:195], v[236:237] op_sel:[1,0,0]
	v_pk_fma_f32 v[236:237], v[74:75], v[198:199], v[236:237] op_sel_hi:[0,1,1]
	v_pk_fma_f32 v[236:237], v[74:75], v[202:203], v[236:237] op_sel:[1,0,0]
	s_nop 0
	v_add_f32_dpp v234, v234, v234 quad_perm:[1,0,3,2] row_mask:0xf bank_mask:0xf
	v_add_f32_dpp v235, v235, v235 quad_perm:[1,0,3,2] row_mask:0xf bank_mask:0xf
	v_add_f32_dpp v236, v236, v236 quad_perm:[1,0,3,2] row_mask:0xf bank_mask:0xf
	v_add_f32_dpp v237, v237, v237 quad_perm:[1,0,3,2] row_mask:0xf bank_mask:0xf
	v_add_f32_dpp v234, v234, v234 quad_perm:[2,3,0,1] row_mask:0xf bank_mask:0xf
	v_add_f32_dpp v235, v235, v235 quad_perm:[2,3,0,1] row_mask:0xf bank_mask:0xf
	v_add_f32_dpp v236, v236, v236 quad_perm:[2,3,0,1] row_mask:0xf bank_mask:0xf
	v_add_f32_dpp v237, v237, v237 quad_perm:[2,3,0,1] row_mask:0xf bank_mask:0xf
	v_add_f32_dpp v234, v234, v234 row_half_mirror row_mask:0xf bank_mask:0xf
	v_add_f32_dpp v235, v235, v235 row_half_mirror row_mask:0xf bank_mask:0xf
	v_add_f32_dpp v236, v236, v236 row_half_mirror row_mask:0xf bank_mask:0xf
	v_add_f32_dpp v237, v237, v237 row_half_mirror row_mask:0xf bank_mask:0xf
	v_add_f32_dpp v234, v234, v234 row_mirror row_mask:0xf bank_mask:0xf
	v_add_f32_dpp v235, v235, v235 row_mirror row_mask:0xf bank_mask:0xf
	v_add_f32_dpp v236, v236, v236 row_mirror row_mask:0xf bank_mask:0xf
	v_add_f32_dpp v237, v237, v237 row_mirror row_mask:0xf bank_mask:0xf
	s_waitcnt vmcnt(9)
	v_pk_add_f32 v[104:105], v[104:105], v[136:137] op_sel_hi:[1,0]
	v_pk_add_f32 v[106:107], v[106:107], v[136:137] op_sel_hi:[1,0]
	v_cmp_ge_u32_e32 vcc, 0, v82
	s_nop 1
	v_cndmask_b32_e32 v104, v109, v104, vcc
	v_cmp_ge_u32_e32 vcc, 1, v82
	s_nop 1
	v_cndmask_b32_e32 v105, v109, v105, vcc
	v_cmp_ge_u32_e32 vcc, 2, v82
	s_nop 1
	v_cndmask_b32_e32 v106, v109, v106, vcc
	v_cmp_ge_u32_e32 vcc, 3, v82
	s_nop 1
	v_cndmask_b32_e32 v107, v109, v107, vcc
	v_pk_fma_f32 v[238:239], v[76:77], v[188:189], v[104:105] op_sel_hi:[0,1,1]
	v_pk_fma_f32 v[238:239], v[76:77], v[192:193], v[238:239] op_sel:[1,0,0]
	v_pk_fma_f32 v[238:239], v[78:79], v[196:197], v[238:239] op_sel_hi:[0,1,1]
	v_pk_fma_f32 v[238:239], v[78:79], v[200:201], v[238:239] op_sel:[1,0,0]
	v_pk_fma_f32 v[240:241], v[76:77], v[190:191], v[106:107] op_sel_hi:[0,1,1]
	v_pk_fma_f32 v[240:241], v[76:77], v[194:195], v[240:241] op_sel:[1,0,0]
	v_pk_fma_f32 v[240:241], v[78:79], v[198:199], v[240:241] op_sel_hi:[0,1,1]
	v_pk_fma_f32 v[240:241], v[78:79], v[202:203], v[240:241] op_sel:[1,0,0]
	s_nop 0
	v_add_f32_dpp v238, v238, v238 quad_perm:[1,0,3,2] row_mask:0xf bank_mask:0xf
	v_add_f32_dpp v239, v239, v239 quad_perm:[1,0,3,2] row_mask:0xf bank_mask:0xf
	v_add_f32_dpp v240, v240, v240 quad_perm:[1,0,3,2] row_mask:0xf bank_mask:0xf
	v_add_f32_dpp v241, v241, v241 quad_perm:[1,0,3,2] row_mask:0xf bank_mask:0xf
	v_add_f32_dpp v238, v238, v238 quad_perm:[2,3,0,1] row_mask:0xf bank_mask:0xf
	v_add_f32_dpp v239, v239, v239 quad_perm:[2,3,0,1] row_mask:0xf bank_mask:0xf
	v_add_f32_dpp v240, v240, v240 quad_perm:[2,3,0,1] row_mask:0xf bank_mask:0xf
	v_add_f32_dpp v241, v241, v241 quad_perm:[2,3,0,1] row_mask:0xf bank_mask:0xf
; DI float fexp2(float x) { return __builtin_amdgcn_exp2f(x); }
; DI float dot16(f32x4 a, f32x4 b) { float d = (a[0] * b[0] + a[1] * b[1]) + (a[2] * b[2] + a[3] * b[3]); d += __shfl_xor(d, 1); d += __shfl_xor(d, 2); d += __shfl_xor(d, 4); d += __shfl_xor(d, 8); return d; }
; DI void unit_sample_attn2(int u, const bf16* __restrict__ Q, const float* __restrict__ ckw, const float* __restrict__ cvw, const float* __restrict__ nkw, const float* __restrict__ nvw, const bf16* __restrict__ G, bf16* __restrict__ MIX, ...
;     ...
;         for (int jj = 0; jj < 4; ++jj) { float s[9]; float mn = NEG;
; #pragma unroll
;             for (int i = 0; i < 9; ++i) { const int dlt = 2048 + jj - idxs[i];
;                 const int cnt = (dlt <= 128 ? 1 : 0) + ((dlt & 3) == 0 ? 1 : 0) + ((dlt & 15) == 0 ? 1 : 0);
;                 const float lc = (cnt == 3) ? 1.5849625f : (cnt == 2) ? 1.f : 0.f;
;                 const float d = dot16(q[jj], kv[i]);
;                 s[i] = (idxs[i] > 2051 || dlt < 0 || cnt == 0) ? NEG : d - slope2 * (float)dlt + lc; mn = fmaxf(mn, s[i]); }
;             float ps = 0.f; f32x4 acc = (f32x4){0.f, 0.f, 0.f, 0.f};
; #pragma unroll
;             for (int i = 0; i < 9; ++i) { const float p = (s[i] <= NEG) ? 0.f : fexp2(s[i] - mn); ps += p; acc += vv[i] * p; }
	v_add_f32_dpp v238, v238, v238 row_half_mirror row_mask:0xf bank_mask:0xf
	v_add_f32_dpp v239, v239, v239 row_half_mirror row_mask:0xf bank_mask:0xf
	v_add_f32_dpp v240, v240, v240 row_half_mirror row_mask:0xf bank_mask:0xf
	v_add_f32_dpp v241, v241, v241 row_half_mirror row_mask:0xf bank_mask:0xf
	v_add_f32_dpp v238, v238, v238 row_mirror row_mask:0xf bank_mask:0xf
	v_add_f32_dpp v239, v239, v239 row_mirror row_mask:0xf bank_mask:0xf
	v_add_f32_dpp v240, v240, v240 row_mirror row_mask:0xf bank_mask:0xf
	v_add_f32_dpp v241, v241, v241 row_mirror row_mask:0xf bank_mask:0xf
	v_max3_f32 v110, v204, v208, v212
	v_max3_f32 v111, v205, v209, v213
	v_max3_f32 v112, v206, v210, v214
	v_max3_f32 v113, v207, v211, v215
	v_max3_f32 v110, v110, v216, v220
	v_max3_f32 v111, v111, v217, v221
	v_max3_f32 v112, v112, v218, v222
	v_max3_f32 v113, v113, v219, v223
	v_max3_f32 v110, v110, v224, v230
	v_max3_f32 v111, v111, v225, v231
	v_max3_f32 v112, v112, v228, v232
	v_max3_f32 v113, v113, v229, v233
	v_max3_f32 v110, v110, v234, v238
	v_max3_f32 v111, v111, v235, v239
	v_max3_f32 v112, v112, v236, v240
	v_max3_f32 v113, v113, v237, v241
	v_pk_add_f32 v[204:205], v[204:205], v[110:111] neg_lo:[0,1] neg_hi:[0,1]
	v_pk_add_f32 v[206:207], v[206:207], v[112:113] neg_lo:[0,1] neg_hi:[0,1]
	v_pk_add_f32 v[208:209], v[208:209], v[110:111] neg_lo:[0,1] neg_hi:[0,1]
	v_pk_add_f32 v[210:211], v[210:211], v[112:113] neg_lo:[0,1] neg_hi:[0,1]
	v_pk_add_f32 v[212:213], v[212:213], v[110:111] neg_lo:[0,1] neg_hi:[0,1]
	v_pk_add_f32 v[214:215], v[214:215], v[112:113] neg_lo:[0,1] neg_hi:[0,1]
	v_pk_add_f32 v[216:217], v[216:217], v[110:111] neg_lo:[0,1] neg_hi:[0,1]
	v_pk_add_f32 v[218:219], v[218:219], v[112:113] neg_lo:[0,1] neg_hi:[0,1]
	v_pk_add_f32 v[220:221], v[220:221], v[110:111] neg_lo:[0,1] neg_hi:[0,1]
	v_pk_add_f32 v[222:223], v[222:223], v[112:113] neg_lo:[0,1] neg_hi:[0,1]
	v_pk_add_f32 v[224:225], v[224:225], v[110:111] neg_lo:[0,1] neg_hi:[0,1]
	v_pk_add_f32 v[228:229], v[228:229], v[112:113] neg_lo:[0,1] neg_hi:[0,1]
	v_pk_add_f32 v[230:231], v[230:231], v[110:111] neg_lo:[0,1] neg_hi:[0,1]
	v_pk_add_f32 v[232:233], v[232:233], v[112:113] neg_lo:[0,1] neg_hi:[0,1]
	v_pk_add_f32 v[234:235], v[234:235], v[110:111] neg_lo:[0,1] neg_hi:[0,1]
	v_pk_add_f32 v[236:237], v[236:237], v[112:113] neg_lo:[0,1] neg_hi:[0,1]
	v_pk_add_f32 v[238:239], v[238:239], v[110:111] neg_lo:[0,1] neg_hi:[0,1]
	v_pk_add_f32 v[240:241], v[240:241], v[112:113] neg_lo:[0,1] neg_hi:[0,1]
	v_exp_f32_e32 v204, v204
	v_exp_f32_e32 v205, v205
	v_exp_f32_e32 v206, v206
	v_exp_f32_e32 v207, v207
	v_exp_f32_e32 v208, v208
	v_exp_f32_e32 v209, v209
	v_exp_f32_e32 v210, v210
	v_exp_f32_e32 v211, v211
	v_exp_f32_e32 v212, v212
	v_exp_f32_e32 v213, v213
	v_exp_f32_e32 v214, v214
	v_exp_f32_e32 v215, v215
	v_exp_f32_e32 v216, v216
	v_exp_f32_e32 v217, v217
	v_exp_f32_e32 v218, v218
	v_exp_f32_e32 v219, v219
	v_exp_f32_e32 v220, v220
	v_exp_f32_e32 v221, v221
	v_exp_f32_e32 v222, v222
	v_exp_f32_e32 v223, v223
	v_exp_f32_e32 v224, v224
	v_exp_f32_e32 v225, v225
	v_exp_f32_e32 v228, v228
	v_exp_f32_e32 v229, v229
	v_exp_f32_e32 v230, v230
	v_exp_f32_e32 v231, v231
	v_exp_f32_e32 v232, v232
	v_exp_f32_e32 v233, v233
	v_exp_f32_e32 v234, v234
	v_exp_f32_e32 v235, v235
	v_exp_f32_e32 v236, v236
	v_exp_f32_e32 v237, v237
	v_exp_f32_e32 v238, v238
	v_exp_f32_e32 v239, v239
	v_exp_f32_e32 v240, v240
	v_exp_f32_e32 v241, v241
	s_waitcnt vmcnt(0)
	v_pk_add_f32 v[114:115], v[204:205], v[208:209]
	v_pk_add_f32 v[116:117], v[206:207], v[210:211]
	v_pk_add_f32 v[114:115], v[114:115], v[212:213]
	v_pk_add_f32 v[116:117], v[116:117], v[214:215]
	v_pk_add_f32 v[114:115], v[114:115], v[216:217]
	v_pk_add_f32 v[116:117], v[116:117], v[218:219]
	v_pk_add_f32 v[114:115], v[114:115], v[220:221]
	v_pk_add_f32 v[116:117], v[116:117], v[222:223]
	v_pk_add_f32 v[114:115], v[114:115], v[224:225]
	v_pk_add_f32 v[116:117], v[116:117], v[228:229]
	v_pk_add_f32 v[114:115], v[114:115], v[230:231]
	v_pk_add_f32 v[116:117], v[116:117], v[232:233]
	v_pk_add_f32 v[114:115], v[114:115], v[234:235]
	v_pk_add_f32 v[116:117], v[116:117], v[236:237]
	v_pk_add_f32 v[114:115], v[114:115], v[238:239]
	v_pk_add_f32 v[116:117], v[116:117], v[240:241]
	v_pk_mul_f32 v[88:89], v[8:9], v[204:205] op_sel_hi:[1,0]
	v_pk_mul_f32 v[90:91], v[10:11], v[204:205] op_sel_hi:[1,0]
	v_pk_mul_f32 v[92:93], v[8:9], v[204:205] op_sel:[0,1] op_sel_hi:[1,1]
	v_pk_mul_f32 v[94:95], v[10:11], v[204:205] op_sel:[0,1] op_sel_hi:[1,1]
	v_pk_mul_f32 v[96:97], v[8:9], v[206:207] op_sel_hi:[1,0]
	v_pk_mul_f32 v[98:99], v[10:11], v[206:207] op_sel_hi:[1,0]
	v_pk_mul_f32 v[100:101], v[8:9], v[206:207] op_sel:[0,1] op_sel_hi:[1,1]
	v_pk_mul_f32 v[102:103], v[10:11], v[206:207] op_sel:[0,1] op_sel_hi:[1,1]
	v_pk_fma_f32 v[88:89], v[12:13], v[208:209], v[88:89] op_sel_hi:[1,0,1]
	v_pk_fma_f32 v[90:91], v[14:15], v[208:209], v[90:91] op_sel_hi:[1,0,1]
	v_pk_fma_f32 v[92:93], v[12:13], v[208:209], v[92:93] op_sel:[0,1,0] op_sel_hi:[1,1,1]
	v_pk_fma_f32 v[94:95], v[14:15], v[208:209], v[94:95] op_sel:[0,1,0] op_sel_hi:[1,1,1]
	v_pk_fma_f32 v[96:97], v[12:13], v[210:211], v[96:97] op_sel_hi:[1,0,1]
	v_pk_fma_f32 v[98:99], v[14:15], v[210:211], v[98:99] op_sel_hi:[1,0,1]
	v_pk_fma_f32 v[100:101], v[12:13], v[210:211], v[100:101] op_sel:[0,1,0] op_sel_hi:[1,1,1]
; #define LAS __attribute__((address_space(3)))
; DI float fexp2(float x) { return __builtin_amdgcn_exp2f(x); }
; DI void unit_sample_attn2(int u, const bf16* __restrict__ Q, const float* __restrict__ ckw, const float* __restrict__ cvw, const float* __restrict__ nkw, const float* __restrict__ nvw, const bf16* __restrict__ G, bf16* __restrict__ MIX, ...
;     ...
;             float ps = 0.f; f32x4 acc = (f32x4){0.f, 0.f, 0.f, 0.f};
; #pragma unroll
;             for (int i = 0; i < 9; ++i) { const float p = (s[i] <= NEG) ? 0.f : fexp2(s[i] - mn); ps += p; acc += vv[i] * p; }
;             *(LAS f32x4*)(pA + (pst * 4 + jj) * 128 + (lane & 31) * 4) = acc;
;             if ((lane & 15) == 0) { sA[(pst * 4 + jj) * 2 + hl] = mn; sA[128 + (pst * 4 + jj) * 2 + hl] = ps; } }
;     }
;     *(LAS f32x4*)(pB + pst * 128 + (lane & 31) * 4) = oB;
;     if ((lane & 15) == 0) { sB[pst * 2 + hl] = mB; sB[32 + pst * 2 + hl] = lB; }
	v_pk_fma_f32 v[102:103], v[14:15], v[210:211], v[102:103] op_sel:[0,1,0] op_sel_hi:[1,1,1]
	v_pk_fma_f32 v[88:89], v[16:17], v[212:213], v[88:89] op_sel_hi:[1,0,1]
	v_pk_fma_f32 v[90:91], v[18:19], v[212:213], v[90:91] op_sel_hi:[1,0,1]
	v_pk_fma_f32 v[92:93], v[16:17], v[212:213], v[92:93] op_sel:[0,1,0] op_sel_hi:[1,1,1]
	v_pk_fma_f32 v[94:95], v[18:19], v[212:213], v[94:95] op_sel:[0,1,0] op_sel_hi:[1,1,1]
	v_pk_fma_f32 v[96:97], v[16:17], v[214:215], v[96:97] op_sel_hi:[1,0,1]
	v_pk_fma_f32 v[98:99], v[18:19], v[214:215], v[98:99] op_sel_hi:[1,0,1]
	v_pk_fma_f32 v[100:101], v[16:17], v[214:215], v[100:101] op_sel:[0,1,0] op_sel_hi:[1,1,1]
	v_pk_fma_f32 v[102:103], v[18:19], v[214:215], v[102:103] op_sel:[0,1,0] op_sel_hi:[1,1,1]
	v_pk_fma_f32 v[88:89], v[20:21], v[216:217], v[88:89] op_sel_hi:[1,0,1]
	v_pk_fma_f32 v[90:91], v[22:23], v[216:217], v[90:91] op_sel_hi:[1,0,1]
	v_pk_fma_f32 v[92:93], v[20:21], v[216:217], v[92:93] op_sel:[0,1,0] op_sel_hi:[1,1,1]
	v_pk_fma_f32 v[94:95], v[22:23], v[216:217], v[94:95] op_sel:[0,1,0] op_sel_hi:[1,1,1]
	v_pk_fma_f32 v[96:97], v[20:21], v[218:219], v[96:97] op_sel_hi:[1,0,1]
	v_pk_fma_f32 v[98:99], v[22:23], v[218:219], v[98:99] op_sel_hi:[1,0,1]
	v_pk_fma_f32 v[100:101], v[20:21], v[218:219], v[100:101] op_sel:[0,1,0] op_sel_hi:[1,1,1]
	v_pk_fma_f32 v[102:103], v[22:23], v[218:219], v[102:103] op_sel:[0,1,0] op_sel_hi:[1,1,1]
	v_pk_fma_f32 v[88:89], v[24:25], v[220:221], v[88:89] op_sel_hi:[1,0,1]
	v_pk_fma_f32 v[90:91], v[26:27], v[220:221], v[90:91] op_sel_hi:[1,0,1]
	v_pk_fma_f32 v[92:93], v[24:25], v[220:221], v[92:93] op_sel:[0,1,0] op_sel_hi:[1,1,1]
	v_pk_fma_f32 v[94:95], v[26:27], v[220:221], v[94:95] op_sel:[0,1,0] op_sel_hi:[1,1,1]
	v_pk_fma_f32 v[96:97], v[24:25], v[222:223], v[96:97] op_sel_hi:[1,0,1]
	v_pk_fma_f32 v[98:99], v[26:27], v[222:223], v[98:99] op_sel_hi:[1,0,1]
	v_pk_fma_f32 v[100:101], v[24:25], v[222:223], v[100:101] op_sel:[0,1,0] op_sel_hi:[1,1,1]
	v_pk_fma_f32 v[102:103], v[26:27], v[222:223], v[102:103] op_sel:[0,1,0] op_sel_hi:[1,1,1]
	v_pk_fma_f32 v[88:89], v[28:29], v[224:225], v[88:89] op_sel_hi:[1,0,1]
	v_pk_fma_f32 v[90:91], v[30:31], v[224:225], v[90:91] op_sel_hi:[1,0,1]
	v_pk_fma_f32 v[92:93], v[28:29], v[224:225], v[92:93] op_sel:[0,1,0] op_sel_hi:[1,1,1]
	v_pk_fma_f32 v[94:95], v[30:31], v[224:225], v[94:95] op_sel:[0,1,0] op_sel_hi:[1,1,1]
	v_pk_fma_f32 v[96:97], v[28:29], v[228:229], v[96:97] op_sel_hi:[1,0,1]
	v_pk_fma_f32 v[98:99], v[30:31], v[228:229], v[98:99] op_sel_hi:[1,0,1]
	v_pk_fma_f32 v[100:101], v[28:29], v[228:229], v[100:101] op_sel:[0,1,0] op_sel_hi:[1,1,1]
	v_pk_fma_f32 v[102:103], v[30:31], v[228:229], v[102:103] op_sel:[0,1,0] op_sel_hi:[1,1,1]
	v_pk_fma_f32 v[88:89], v[32:33], v[230:231], v[88:89] op_sel_hi:[1,0,1]
	v_pk_fma_f32 v[90:91], v[34:35], v[230:231], v[90:91] op_sel_hi:[1,0,1]
	v_pk_fma_f32 v[92:93], v[32:33], v[230:231], v[92:93] op_sel:[0,1,0] op_sel_hi:[1,1,1]
	v_pk_fma_f32 v[94:95], v[34:35], v[230:231], v[94:95] op_sel:[0,1,0] op_sel_hi:[1,1,1]
	v_pk_fma_f32 v[96:97], v[32:33], v[232:233], v[96:97] op_sel_hi:[1,0,1]
	v_pk_fma_f32 v[98:99], v[34:35], v[232:233], v[98:99] op_sel_hi:[1,0,1]
	v_pk_fma_f32 v[100:101], v[32:33], v[232:233], v[100:101] op_sel:[0,1,0] op_sel_hi:[1,1,1]
	v_pk_fma_f32 v[102:103], v[34:35], v[232:233], v[102:103] op_sel:[0,1,0] op_sel_hi:[1,1,1]
	v_pk_fma_f32 v[88:89], v[36:37], v[234:235], v[88:89] op_sel_hi:[1,0,1]
	v_pk_fma_f32 v[90:91], v[38:39], v[234:235], v[90:91] op_sel_hi:[1,0,1]
	v_pk_fma_f32 v[92:93], v[36:37], v[234:235], v[92:93] op_sel:[0,1,0] op_sel_hi:[1,1,1]
	v_pk_fma_f32 v[94:95], v[38:39], v[234:235], v[94:95] op_sel:[0,1,0] op_sel_hi:[1,1,1]
	v_pk_fma_f32 v[96:97], v[36:37], v[236:237], v[96:97] op_sel_hi:[1,0,1]
	v_pk_fma_f32 v[98:99], v[38:39], v[236:237], v[98:99] op_sel_hi:[1,0,1]
	v_pk_fma_f32 v[100:101], v[36:37], v[236:237], v[100:101] op_sel:[0,1,0] op_sel_hi:[1,1,1]
	v_pk_fma_f32 v[102:103], v[38:39], v[236:237], v[102:103] op_sel:[0,1,0] op_sel_hi:[1,1,1]
	v_pk_fma_f32 v[88:89], v[40:41], v[238:239], v[88:89] op_sel_hi:[1,0,1]
	v_pk_fma_f32 v[90:91], v[42:43], v[238:239], v[90:91] op_sel_hi:[1,0,1]
	v_pk_fma_f32 v[92:93], v[40:41], v[238:239], v[92:93] op_sel:[0,1,0] op_sel_hi:[1,1,1]
	v_pk_fma_f32 v[94:95], v[42:43], v[238:239], v[94:95] op_sel:[0,1,0] op_sel_hi:[1,1,1]
	v_pk_fma_f32 v[96:97], v[40:41], v[240:241], v[96:97] op_sel_hi:[1,0,1]
	v_pk_fma_f32 v[98:99], v[42:43], v[240:241], v[98:99] op_sel_hi:[1,0,1]
	v_pk_fma_f32 v[100:101], v[40:41], v[240:241], v[100:101] op_sel:[0,1,0] op_sel_hi:[1,1,1]
	v_pk_fma_f32 v[102:103], v[42:43], v[240:241], v[102:103] op_sel:[0,1,0] op_sel_hi:[1,1,1]
	ds_write_b128 v83, v[88:91] offset:0
	ds_write_b128 v83, v[92:95] offset:512
	ds_write_b128 v83, v[96:99] offset:1024
	ds_write_b128 v83, v[100:103] offset:1536
	ds_write_b128 v84, v[4:7] offset:32768
	s_and_saveexec_b64 s[2:3], s[20:21]
	ds_write_b32 v86, v110 offset:40960
	ds_write_b32 v86, v114 offset:41472
	ds_write_b32 v86, v111 offset:40968
	ds_write_b32 v86, v115 offset:41480
	ds_write_b32 v86, v112 offset:40976
	ds_write_b32 v86, v116 offset:41488
	ds_write_b32 v86, v113 offset:40984
	ds_write_b32 v86, v117 offset:41496
	ds_write_b32 v118, v85 offset:41984
	ds_write_b32 v118, v87 offset:42112
	s_branch .LBB0_720
